# retention outputs: LDS ladders software-pipelined (reads of the next MFMA group issued before this group's MFMAs, alternate fragment registers v172-187), on top of v28
# speedup vs baseline: 1.0057x; 1.0033x over previous
; #define RLAS __attribute__((address_space(3)))
; #define LBAR() do { asm volatile("s_waitcnt lgkmcnt(0)" ::: "memory"); __builtin_amdgcn_s_barrier(); asm volatile("" ::: "memory"); } while (0)
; __device__ __forceinline__ void out_unit(RLAS unsigned char* L, int b, int h, int c, const bf16_t* QR, bf16_t* PR, const bf16_t* KR, const bf16_t* VR, const bf16_t* GR, const bf16_t* ST, size_t stbatch, const float* gnw, float lgf, float lgb, OutRegs& PF, bool is_first, bool has_next, int nb, int nh ...
;     ...
;     const size_t tok0 = (size_t)b * SEQ + (size_t)c * 128;
;     const int srow = tid >> 2, sqt = tid & 3;
;     const int grow = (tid >> 6) * 16 + ((tid >> 4) & 3), gch = tid & 15;
;     RLAS unsigned char* R2 = L + REG1 + REGV;
; #pragma unroll
;     for (int i = 0; i < 4; ++i) { *(RLAS u32x4*)(R2 + (grow + 4 * i) * RS + gch * 16) = PF.q[i]; *(RLAS u32x4*)(R0 + (grow + 4 * i) * RS + gch * 16) = PF.k[i]; *(RLAS u32x4*)(R1 + (grow + 4 * i) * RSV + gch * 16) = PF.v[i]; }
;     asm volatile("" ::: "memory"); __builtin_amdgcn_sched_barrier(0);
;     u32x4 sfr[4], sbr[4];
;     { const bf16_t* sf = ST + (size_t)b * stbatch + ((size_t)(0 * 4 + h) * 32 + c) * 16384 + (size_t)grow * 128 + gch * 8;
;       const bf16_t* sb = ST + (size_t)b * stbatch + ((size_t)(1 * 4 + h) * 32 + c) * 16384 + (size_t)grow * 128 + gch * 8;
; #pragma unroll
;       for (int i = 0; i < 4; ++i) { sfr[i] = *(const u32x4*)(sf + (size_t)(4 * i) * 128); sbr[i] = *(const u32x4*)(sb + (size_t)(4 * i) * 128); } }
;     LBAR();
; __global__ void __launch_bounds__(NWAVES * 64, 2) mega_fwd(Args args) {
;     ...
;                 const int b = U >> 7, h = (U >> 5) & 3, c = U & 31;
;                 const float lgf = -log2f(1.f + expf(-dec_f[l * 4 + h])), lgb = -log2f(1.f + expf(-dec_b[l * 4 + h]));
;                 ret_body::out_unit(L + RING_OFF, b, h, c, QR, rep ? (bf16_t*)out + ST_BATCH / 2 + (size_t)b * (ST_BATCH / 2) : QR, KR, VR, GR, STp, stbatch, gnw + l * 512, lgf, lgb, PF, i == 0, Un >= 0, Un >> 7, (Un >> 5) & 3, Un & 31);
.LBB0_502:
	s_bfe_u32 s15, s6, 0x20005
	s_or_b32 s16, s15, s9
	v_readlane_b32 s52, v252, 10
	s_ashr_i32 s0, s6, 7
	s_and_b32 s20, s6, 31
	s_lshl_b64 s[6:7], s[16:17], 2
	v_readlane_b32 s62, v252, 20
	v_readlane_b32 s63, v252, 21
	s_add_u32 s22, s62, s6
	s_addc_u32 s23, s63, s7
	global_load_dword v2, v3, s[22:23]
	s_mov_b32 s5, 0xbfb8aa3b
	s_mov_b32 s16, 0x42ce8ed0
	s_mov_b32 s21, 0xc2b17218
	v_readlane_b32 s64, v252, 22
	v_readlane_b32 s65, v252, 23
	v_mov_b32_e32 v140, v0
	v_readlane_b32 s37, v255, 0
	s_movk_i32 s33, 0x110
	v_readlane_b32 s53, v252, 11
	v_readlane_b32 s54, v252, 12
	v_readlane_b32 s55, v252, 13
	v_readlane_b32 s56, v252, 14
	v_readlane_b32 s57, v252, 15
	v_readlane_b32 s58, v252, 16
	v_readlane_b32 s59, v252, 17
	v_readlane_b32 s60, v252, 18
	v_readlane_b32 s61, v252, 19
	v_readlane_b32 s66, v252, 24
	v_readlane_b32 s67, v252, 25
	s_waitcnt vmcnt(0)
	v_mul_f32_e32 v52, 0xbfb8aa3b, v2
	v_fma_f32 v53, v2, s5, -v52
	v_rndne_f32_e32 v54, v52
	v_fmac_f32_e32 v53, 0xb2a5705f, v2
	v_sub_f32_e32 v52, v52, v54
	v_add_f32_e32 v52, v52, v53
	v_cvt_i32_f32_e32 v54, v54
	v_exp_f32_e32 v52, v52
	v_cmp_nlt_f32_e32 vcc, s16, v2
	v_ldexp_f32 v52, v52, v54
	s_nop 0
	v_cndmask_b32_e32 v52, 0, v52, vcc
	v_cmp_ngt_f32_e32 vcc, s21, v2
	s_nop 1
	v_cndmask_b32_e32 v2, v225, v52, vcc
	v_add_f32_e32 v2, 1.0, v2
	v_cmp_gt_f32_e32 vcc, s35, v2
	s_and_b64 s[22:23], vcc, exec
	s_cselect_b32 s1, 32, 0
	s_add_u32 s6, s64, s6
	s_addc_u32 s7, s65, s7
	global_load_dword v56, v3, s[6:7]
	v_ldexp_f32 v2, v2, s1
	v_log_f32_e32 v54, v2
	v_cndmask_b32_e32 v53, 0, v226, vcc
	v_ashrrev_i32_e32 v2, 6, v140
	v_bfe_u32 v52, v140, 4, 2
	v_and_b32_e32 v148, 15, v140
	v_readfirstlane_b32 s14, v2
	v_lshl_or_b32 v144, v2, 4, v52
	v_lshlrev_b32_e32 v2, 4, v148
	v_add_u32_e32 v57, s37, v2
	v_mul_lo_u32 v58, v144, s33
	v_add_u32_e32 v52, 0, v2
	v_sub_f32_e32 v149, v54, v53
	v_add_u32_e32 v53, v57, v58
	s_movk_i32 s1, 0x140
	v_mad_u64_u32 v[54:55], s[6:7], v144, s1, v[52:53]
	v_add_u32_e32 v55, 0x440, v58
	v_add_u32_e32 v136, v52, v58
	v_add_u32_e32 v59, 0x880, v58
	ds_write_b128 v53, v[16:19]
	ds_write_b128 v136, v[4:7]
	ds_write_b128 v54, v[8:11] offset:34816
	v_add_u32_e32 v4, v57, v55
	v_add_u32_e32 v137, v52, v55
	v_add_u32_e32 v5, v57, v59
	v_add_u32_e32 v138, v52, v59
	ds_write_b128 v4, v[12:15]
	ds_write_b128 v137, v[20:23]
	ds_write_b128 v54, v[28:31] offset:36096
	ds_write_b128 v5, v[40:43]
	ds_write_b128 v138, v[32:35]
	ds_write_b128 v54, v[36:39] offset:37376
	v_add_u32_e32 v58, 0xcc0, v58
	v_add_u32_e32 v6, v57, v58
	v_add_u32_e32 v139, v52, v58
	ds_write_b128 v6, v[24:27]
	ds_write_b128 v139, v[48:51]
	ds_write_b128 v54, v[44:47] offset:38656
	v_bfe_u32 v147, v140, 5, 1
	v_lshrrev_b32_e32 v141, 2, v140
	s_waitcnt vmcnt(0)
	v_mul_f32_e32 v4, 0xbfb8aa3b, v56
	v_fma_f32 v5, v56, s5, -v4
	v_rndne_f32_e32 v7, v4
	v_fmac_f32_e32 v5, 0xb2a5705f, v56
	v_sub_f32_e32 v4, v4, v7
	v_add_f32_e32 v4, v4, v5
	v_cvt_i32_f32_e32 v7, v7
	v_exp_f32_e32 v4, v4
	v_cmp_nlt_f32_e32 vcc, s16, v56
	v_ldexp_f32 v4, v4, v7
	s_nop 0
	v_cndmask_b32_e32 v4, 0, v4, vcc
	v_cmp_ngt_f32_e32 vcc, s21, v56
	s_nop 1
	v_cndmask_b32_e32 v4, v225, v4, vcc
	v_add_f32_e32 v4, 1.0, v4
	v_cmp_gt_f32_e32 vcc, s35, v4
	s_and_b64 s[6:7], vcc, exec
	s_cselect_b32 s5, 32, 0
	s_ashr_i32 s1, s0, 31
	v_ldexp_f32 v4, v4, s5
	s_lshl_b64 s[4:5], s[0:1], s4
	s_ashr_i32 s21, s27, 7
	s_bfe_u32 s22, s27, 0x20005
	s_and_b32 s23, s27, 31
	s_lshl_b32 s16, s20, 7
	s_lshl_b64 s[6:7], s[0:1], 12
	s_lshl_b64 s[4:5], s[4:5], 1
	v_readlane_b32 s1, v253, 33
	s_add_u32 s1, s1, s4
	v_readlane_b32 s4, v253, 32
	s_addc_u32 s4, s4, s5
	s_lshl_b32 s5, s20, 15
	s_lshl_b32 s26, s15, 20
	s_or_b32 s5, s26, s5
	s_add_u32 s28, s1, s5
	s_addc_u32 s29, s4, 0
	s_lshl_b32 s1, s14, 6
	s_and_b32 s26, s1, 64
	v_log_f32_e32 v4, v4
	s_lshl_b32 s30, s14, 4
	s_lshl_b32 s1, s26, 2
	s_or_b32 s6, s6, s16
	s_lshl_b32 s16, s15, 8
	s_lshl_b32 s4, s15, 9
	s_and_b32 s14, s30, 0xffffffe0
	s_add_i32 s1, s1, 0
	s_add_u32 s4, s10, s4
	v_cndmask_b32_e32 v5, 0, v226, vcc
	s_addc_u32 s5, s11, 0
	v_sub_f32_e32 v150, v4, v5
	s_cmp_gt_i32 s27, -1
	v_ashrrev_i32_e32 v145, 31, v144
	v_lshlrev_b64 v[4:5], 8, v[144:145]
	v_lshl_add_u64 v[4:5], s[28:29], 0, v[4:5]
	v_lshl_add_u64 v[4:5], v[4:5], 0, v[2:3]
	s_mov_b32 s27, 0x400000
	v_add_co_u32_e32 v8, vcc, s27, v4
	s_mov_b64 s[28:29], 0x400000
	s_nop 0
	v_addc_co_u32_e32 v9, vcc, 0, v5, vcc
	v_lshl_add_u64 v[6:7], v[4:5], 0, s[28:29]
	global_load_dwordx4 v[72:75], v[4:5], off
	global_load_dwordx4 v[76:79], v[8:9], off
	global_load_dwordx4 v[80:83], v[4:5], off offset:1024
	global_load_dwordx4 v[84:87], v[6:7], off offset:1024
	global_load_dwordx4 v[88:91], v[4:5], off offset:2048
	global_load_dwordx4 v[92:95], v[6:7], off offset:2048
	global_load_dwordx4 v[96:99], v[4:5], off offset:3072
	global_load_dwordx4 v[128:131], v[6:7], off offset:3072
	v_mov_b32_e32 v4, s30
	s_movk_i32 s27, 0xffe0
	v_bfi_b32 v154, s27, v4, v140
	v_mul_lo_u32 v4, v154, s33
	v_lshlrev_b32_e32 v5, 4, v147
	s_waitcnt lgkmcnt(0)
	s_barrier
; #define RLAS __attribute__((address_space(3)))
; #define RMFMA(a, b, c) __builtin_amdgcn_mfma_f32_32x32x16_bf16(a, b, c, 0, 0, 0)
; __device__ __forceinline__ void out_unit(RLAS unsigned char* L, int b, int h, int c, const bf16_t* QR, bf16_t* PR, const bf16_t* KR, const bf16_t* VR, const bf16_t* GR, const bf16_t* ST, size_t stbatch, const float* gnw, float lgf, float lgb, OutRegs& PF, bool is_first, bool has_next, int nb, int nh ...
;     ...
;     bf16x8 qf[8];
; #pragma unroll
;     for (int ks = 0; ks < 8; ++ks) qf[ks] = *(const RLAS bf16x8*)(R2 + (32 * ib + r) * RS + (16 * ks + 8 * h2) * 2);
;     bf16x8 P[4][2];
;     const int iq = 32 * ib + r;
;     float cfm[3], cbp[3];
; #pragma unroll
;     for (int e = 0; e < 3; ++e) { cfm[e] = __builtin_amdgcn_exp2f(-lgf * (float)(e + 1)); cbp[e] = __builtin_amdgcn_exp2f(lgb * (float)(e + 1)); }
;     { f32x16 X[4];
; #pragma unroll
;       for (int jb = 0; jb < 4; ++jb)
; #pragma unroll
;           for (int g = 0; g < 16; ++g) X[jb][g] = 0.f;
; #pragma unroll
;       for (int ks = 0; ks < 8; ++ks) { bf16x8 a[4];
; #pragma unroll
;           for (int jb = 0; jb < 4; ++jb) a[jb] = *(const RLAS bf16x8*)(R0 + (32 * jb + r) * RS + (16 * ks + 8 * h2) * 2);
; #pragma unroll
;           for (int jb = 0; jb < 4; ++jb) X[jb] = RMFMA(a[jb], qf[ks], X[jb]); }
; #pragma unroll
;       for (int jb = 0; jb < 4; ++jb) {
; #pragma unroll
;           for (int q4 = 0; q4 < 4; ++q4) {
;               const int d0 = iq - (32 * jb + 8 * q4 + 4 * h2); const float fd = (float)d0, Ff = __builtin_amdgcn_exp2f(lgf * fd), Fb = __builtin_amdgcn_exp2f(-lgb * fd);
;               X[jb][4 * q4 + 0] *= d0 >= 0 ? Ff : Fb;             X[jb][4 * q4 + 1] *= d0 >= 1 ? Ff * cfm[0] : Fb * cbp[0];
;               X[jb][4 * q4 + 2] *= d0 >= 2 ? Ff * cfm[1] : Fb * cbp[1]; X[jb][4 * q4 + 3] *= d0 >= 3 ? Ff * cfm[2] : Fb * cbp[2]; }
	v_add3_u32 v4, s37, v4, v5
	ds_read_b128 v[68:71], v4
	ds_read_b128 v[124:127], v4 offset:32
	ds_read_b128 v[120:123], v4 offset:64
	ds_read_b128 v[116:119], v4 offset:96
	ds_read_b128 v[112:115], v4 offset:128
	ds_read_b128 v[108:111], v4 offset:160
	ds_read_b128 v[104:107], v4 offset:192
	ds_read_b128 v[100:103], v4 offset:224
	v_add_f32_e32 v4, v149, v149
	v_exp_f32_e32 v132, v4
	v_mul_f32_e32 v4, -2.0, v150
	v_and_b32_e32 v151, 31, v140
	v_exp_f32_e32 v134, v4
	v_mul_f32_e32 v4, 0x40400000, v149
	v_add_u32_e32 v152, 0, v5
	v_exp_f32_e32 v133, v4
	v_mul_f32_e32 v4, 0xc0400000, v150
	v_mad_u32_u24 v153, v151, s33, v152
	v_exp_f32_e32 v135, v4
	ds_read_b128 v[4:7], v153 offset:8704
	ds_read_b128 v[8:11], v153 offset:17408
	ds_read_b128 v[12:15], v153 offset:26112
	ds_read_b128 v[16:19], v153
	ds_read_b128 v[156:159], v153 offset:32
	s_waitcnt lgkmcnt(1)
	v_mfma_f32_32x32x16_bf16 v[52:67], v[16:19], v[68:71], 0
	ds_read_b128 v[160:163], v153 offset:8736
	ds_read_b128 v[164:167], v153 offset:17440
	ds_read_b128 v[168:171], v153 offset:26144
	v_exp_f32_e32 v143, v149
	v_exp_f32_e64 v146, -v150
	v_and_b32_e32 v142, 16, v140
	s_movk_i32 s27, 0x6000
	v_mfma_f32_32x32x16_bf16 v[36:51], v[4:7], v[68:71], 0
	v_mfma_f32_32x32x16_bf16 v[20:35], v[8:11], v[68:71], 0
	v_mfma_f32_32x32x16_bf16 v[4:19], v[12:15], v[68:71], 0
	ds_read_b128 v[172:175], v153 offset:64
	ds_read_b128 v[176:179], v153 offset:8768
	ds_read_b128 v[180:183], v153 offset:17472
	ds_read_b128 v[184:187], v153 offset:26176
	s_waitcnt lgkmcnt(7)
	v_mfma_f32_32x32x16_bf16 v[52:67], v[156:159], v[124:127], v[52:67]
	s_waitcnt lgkmcnt(6)
	v_mfma_f32_32x32x16_bf16 v[36:51], v[160:163], v[124:127], v[36:51]
	s_waitcnt lgkmcnt(5)
	v_mfma_f32_32x32x16_bf16 v[20:35], v[164:167], v[124:127], v[20:35]
	s_waitcnt lgkmcnt(4)
	v_mfma_f32_32x32x16_bf16 v[4:19], v[168:171], v[124:127], v[4:19]
	ds_read_b128 v[156:159], v153 offset:96
	ds_read_b128 v[160:163], v153 offset:8800
	ds_read_b128 v[164:167], v153 offset:17504
	ds_read_b128 v[168:171], v153 offset:26208
	s_waitcnt lgkmcnt(7)
	v_mfma_f32_32x32x16_bf16 v[52:67], v[172:175], v[120:123], v[52:67]
	s_waitcnt lgkmcnt(6)
	v_mfma_f32_32x32x16_bf16 v[36:51], v[176:179], v[120:123], v[36:51]
	s_waitcnt lgkmcnt(5)
	v_mfma_f32_32x32x16_bf16 v[20:35], v[180:183], v[120:123], v[20:35]
	s_waitcnt lgkmcnt(4)
	v_mfma_f32_32x32x16_bf16 v[4:19], v[184:187], v[120:123], v[4:19]
	ds_read_b128 v[172:175], v153 offset:128
	ds_read_b128 v[176:179], v153 offset:8832
	ds_read_b128 v[180:183], v153 offset:17536
	ds_read_b128 v[184:187], v153 offset:26240
	s_waitcnt lgkmcnt(7)
	v_mfma_f32_32x32x16_bf16 v[52:67], v[156:159], v[116:119], v[52:67]
	s_waitcnt lgkmcnt(6)
	v_mfma_f32_32x32x16_bf16 v[36:51], v[160:163], v[116:119], v[36:51]
	s_waitcnt lgkmcnt(5)
	v_mfma_f32_32x32x16_bf16 v[20:35], v[164:167], v[116:119], v[20:35]
	s_waitcnt lgkmcnt(4)
	v_mfma_f32_32x32x16_bf16 v[4:19], v[168:171], v[116:119], v[4:19]
	ds_read_b128 v[156:159], v153 offset:160
	ds_read_b128 v[160:163], v153 offset:8864
	ds_read_b128 v[164:167], v153 offset:17568
	ds_read_b128 v[168:171], v153 offset:26272
	s_waitcnt lgkmcnt(7)
	v_mfma_f32_32x32x16_bf16 v[52:67], v[172:175], v[112:115], v[52:67]
	s_waitcnt lgkmcnt(6)
	v_mfma_f32_32x32x16_bf16 v[36:51], v[176:179], v[112:115], v[36:51]
	s_waitcnt lgkmcnt(5)
	v_mfma_f32_32x32x16_bf16 v[20:35], v[180:183], v[112:115], v[20:35]
	s_waitcnt lgkmcnt(4)
	v_mfma_f32_32x32x16_bf16 v[4:19], v[184:187], v[112:115], v[4:19]
	ds_read_b128 v[172:175], v153 offset:192
	ds_read_b128 v[176:179], v153 offset:8896
	ds_read_b128 v[180:183], v153 offset:17600
	ds_read_b128 v[184:187], v153 offset:26304
	s_waitcnt lgkmcnt(7)
	v_mfma_f32_32x32x16_bf16 v[52:67], v[156:159], v[108:111], v[52:67]
	s_waitcnt lgkmcnt(6)
	v_mfma_f32_32x32x16_bf16 v[36:51], v[160:163], v[108:111], v[36:51]
	s_waitcnt lgkmcnt(5)
	v_mfma_f32_32x32x16_bf16 v[20:35], v[164:167], v[108:111], v[20:35]
	s_waitcnt lgkmcnt(4)
	v_mfma_f32_32x32x16_bf16 v[4:19], v[168:171], v[108:111], v[4:19]
	ds_read_b128 v[156:159], v153 offset:224
	ds_read_b128 v[160:163], v153 offset:8928
	ds_read_b128 v[164:167], v153 offset:17632
	ds_read_b128 v[168:171], v153 offset:26336
	s_waitcnt lgkmcnt(7)
	v_mfma_f32_32x32x16_bf16 v[52:67], v[172:175], v[104:107], v[52:67]
	s_waitcnt lgkmcnt(6)
	v_mfma_f32_32x32x16_bf16 v[36:51], v[176:179], v[104:107], v[36:51]
	s_waitcnt lgkmcnt(5)
	v_mfma_f32_32x32x16_bf16 v[20:35], v[180:183], v[104:107], v[20:35]
	s_waitcnt lgkmcnt(4)
	v_mfma_f32_32x32x16_bf16 v[4:19], v[184:187], v[104:107], v[4:19]
	v_lshlrev_b32_e32 v153, 2, v147
	v_sub_u32_e32 v147, v154, v153
	v_cvt_f32_i32_e32 v155, v147
	v_cmp_gt_i32_e32 vcc, 0, v147
	v_cmp_lt_i32_e64 s[38:39], 0, v147
	v_mul_f32_e64 v154, -v149, v155
	s_waitcnt lgkmcnt(3)
	v_mfma_f32_32x32x16_bf16 v[52:67], v[156:159], v[100:103], v[52:67]
	v_mul_f32_e32 v155, v150, v155
	v_exp_f32_e32 v154, v154
	v_exp_f32_e32 v156, v155
	v_mul_f32_e32 v155, v143, v154
	v_mul_f32_e32 v157, v146, v156
	v_cndmask_b32_e64 v159, v157, v155, s[38:39]
	v_cndmask_b32_e32 v158, v154, v156, vcc
	v_cmp_lt_i32_e32 vcc, 1, v147
	v_cmp_lt_i32_e64 s[38:39], 2, v147
	v_pk_mul_f32 v[154:155], v[132:133], v[154:155] op_sel_hi:[1,0]
	v_pk_mul_f32 v[156:157], v[134:135], v[156:157] op_sel_hi:[1,0]
	s_nop 0
	v_pk_mul_f32 v[52:53], v[158:159], v[52:53]
	v_cndmask_b32_e64 v155, v157, v155, s[38:39]
	v_cndmask_b32_e32 v154, v156, v154, vcc
	v_pk_mul_f32 v[54:55], v[154:155], v[54:55]
	v_add_u32_e32 v155, -8, v147
	v_cvt_f32_i32_e32 v156, v155
	v_cmp_gt_i32_e32 vcc, 0, v155
	v_cmp_lt_i32_e64 s[38:39], 0, v155
	s_waitcnt lgkmcnt(2)
; __device__ __forceinline__ unsigned pkbf(float lo, float hi) { const f32x2r v = {lo, hi}; return __builtin_bit_cast(unsigned, __builtin_convertvector(v, bf16x2r)); }
; __device__ __forceinline__ void out_unit(RLAS unsigned char* L, int b, int h, int c, const bf16_t* QR, bf16_t* PR, const bf16_t* KR, const bf16_t* VR, const bf16_t* GR, const bf16_t* ST, size_t stbatch, const float* gnw, float lgf, float lgb, OutRegs& PF, bool is_first, bool has_next, int nb, int nh ...
;     ...
;       for (int jb = 0; jb < 4; ++jb) {
; #pragma unroll
;           for (int q4 = 0; q4 < 4; ++q4) {
;               const int d0 = iq - (32 * jb + 8 * q4 + 4 * h2); const float fd = (float)d0, Ff = __builtin_amdgcn_exp2f(lgf * fd), Fb = __builtin_amdgcn_exp2f(-lgb * fd);
;               X[jb][4 * q4 + 0] *= d0 >= 0 ? Ff : Fb;             X[jb][4 * q4 + 1] *= d0 >= 1 ? Ff * cfm[0] : Fb * cbp[0];
;               X[jb][4 * q4 + 2] *= d0 >= 2 ? Ff * cfm[1] : Fb * cbp[1]; X[jb][4 * q4 + 3] *= d0 >= 3 ? Ff * cfm[2] : Fb * cbp[2]; }
; #pragma unroll
;           for (int s = 0; s < 2; ++s) { u32x4 pw; pw.x = pkbf(X[jb][8 * s + 0], X[jb][8 * s + 1]); pw.y = pkbf(X[jb][8 * s + 2], X[jb][8 * s + 3]); pw.z = pkbf(X[jb][8 * s + 4], X[jb][8 * s + 5]); pw.w = pkbf(X[jb][8 * s + 6], X[jb][8 * s + 7]);
;               P[jb][s] = __builtin_bit_cast(bf16x8, pw); } } }
	v_mfma_f32_32x32x16_bf16 v[36:51], v[160:163], v[100:103], v[36:51]
	v_mul_f32_e64 v154, -v149, v156
	v_mul_f32_e32 v156, v150, v156
	v_exp_f32_e32 v154, v154
	v_exp_f32_e32 v156, v156
	v_mul_f32_e32 v157, v143, v154
	v_mul_f32_e32 v158, v146, v156
	v_cndmask_b32_e64 v159, v158, v157, s[38:39]
	v_cndmask_b32_e32 v158, v154, v156, vcc
	v_pk_mul_f32 v[158:159], v[158:159], v[56:57]
	v_cmp_lt_i32_e32 vcc, 1, v155
	v_cmp_lt_i32_e64 s[38:39], 2, v155
	v_pk_mul_f32 v[56:57], v[132:133], v[154:155] op_sel_hi:[1,0]
	v_pk_mul_f32 v[154:155], v[134:135], v[156:157] op_sel_hi:[1,0]
	s_waitcnt lgkmcnt(1)
	v_mfma_f32_32x32x16_bf16 v[20:35], v[164:167], v[100:103], v[20:35]
	v_cndmask_b32_e64 v57, v155, v57, s[38:39]
	v_cndmask_b32_e32 v56, v154, v56, vcc
	v_mul_f32_e64 v154, v56, v58
	v_mul_f32_e64 v155, v57, v59
	v_add_u32_e32 v57, -16, v147
	v_cvt_f32_i32_e32 v58, v57
	v_cmp_gt_i32_e32 vcc, 0, v57
	v_cmp_lt_i32_e64 s[38:39], 0, v57
	s_waitcnt lgkmcnt(0)
	v_mfma_f32_32x32x16_bf16 v[4:19], v[168:171], v[100:103], v[4:19]
	v_mul_f32_e64 v56, -v149, v58
	v_mul_f32_e32 v58, v150, v58
	v_exp_f32_e32 v56, v56
	v_exp_f32_e32 v58, v58
	v_mul_f32_e32 v59, v143, v56
	v_mul_f32_e32 v156, v146, v58
	v_cndmask_b32_e64 v157, v156, v59, s[38:39]
	v_cndmask_b32_e32 v156, v56, v58, vcc
	v_cmp_lt_i32_e32 vcc, 1, v57
	v_cmp_lt_i32_e64 s[38:39], 2, v57
	v_pk_mul_f32 v[56:57], v[132:133], v[56:57] op_sel_hi:[1,0]
	v_pk_mul_f32 v[58:59], v[134:135], v[58:59] op_sel_hi:[1,0]
	v_pk_mul_f32 v[60:61], v[156:157], v[60:61]
	v_cndmask_b32_e64 v57, v59, v57, s[38:39]
	v_cndmask_b32_e32 v56, v58, v56, vcc
	v_pk_mul_f32 v[62:63], v[56:57], v[62:63]
	v_subrev_u32_e32 v57, 24, v147
	v_cvt_f32_i32_e32 v58, v57
	v_cmp_gt_i32_e32 vcc, 0, v57
	v_cmp_lt_i32_e64 s[38:39], 0, v57
	v_mul_f32_e64 v56, -v149, v58
	v_mul_f32_e32 v58, v150, v58
	v_exp_f32_e32 v56, v56
	v_exp_f32_e32 v58, v58
	v_mul_f32_e32 v59, v143, v56
	v_mul_f32_e32 v156, v146, v58
	v_cndmask_b32_e64 v157, v156, v59, s[38:39]
	v_cndmask_b32_e32 v156, v56, v58, vcc
	v_cmp_lt_i32_e32 vcc, 1, v57
	v_cmp_lt_i32_e64 s[38:39], 2, v57
	v_pk_mul_f32 v[56:57], v[132:133], v[56:57] op_sel_hi:[1,0]
	v_pk_mul_f32 v[58:59], v[134:135], v[58:59] op_sel_hi:[1,0]
	v_pk_mul_f32 v[64:65], v[156:157], v[64:65]
	v_cndmask_b32_e64 v57, v59, v57, s[38:39]
	v_cndmask_b32_e32 v56, v58, v56, vcc
	v_pk_mul_f32 v[66:67], v[56:57], v[66:67]
	v_cvt_pk_bf16_f32 v56, v52, v53
	v_cvt_pk_bf16_f32 v52, v60, v61
	v_subrev_u32_e32 v61, 32, v147
	v_cvt_pk_bf16_f32 v53, v62, v63
	v_cvt_f32_i32_e32 v62, v61
	v_cvt_pk_bf16_f32 v57, v54, v55
	v_cvt_pk_bf16_f32 v54, v64, v65
	v_cmp_gt_i32_e32 vcc, 0, v61
	v_mul_f32_e64 v60, -v149, v62
	v_mul_f32_e32 v62, v150, v62
	v_exp_f32_e32 v60, v60
	v_exp_f32_e32 v62, v62
	v_cmp_lt_i32_e64 s[38:39], 0, v61
	v_cvt_pk_bf16_f32 v58, v158, v159
	v_mul_f32_e32 v63, v143, v60
	v_mul_f32_e32 v64, v146, v62
	v_cndmask_b32_e64 v65, v64, v63, s[38:39]
	v_cndmask_b32_e32 v64, v60, v62, vcc
	v_cmp_lt_i32_e32 vcc, 1, v61
	v_cmp_lt_i32_e64 s[38:39], 2, v61
	v_pk_mul_f32 v[60:61], v[132:133], v[60:61] op_sel_hi:[1,0]
	v_pk_mul_f32 v[62:63], v[134:135], v[62:63] op_sel_hi:[1,0]
	v_pk_mul_f32 v[36:37], v[64:65], v[36:37]
	v_cndmask_b32_e64 v61, v63, v61, s[38:39]
	v_cndmask_b32_e32 v60, v62, v60, vcc
	v_pk_mul_f32 v[38:39], v[60:61], v[38:39]
	v_subrev_u32_e32 v61, 40, v147
	v_cvt_f32_i32_e32 v62, v61
	v_cmp_gt_i32_e32 vcc, 0, v61
	v_cmp_lt_i32_e64 s[38:39], 0, v61
	v_cvt_pk_bf16_f32 v59, v154, v155
	v_mul_f32_e64 v60, -v149, v62
	v_mul_f32_e32 v62, v150, v62
	v_exp_f32_e32 v60, v60
	v_exp_f32_e32 v62, v62
	v_cvt_pk_bf16_f32 v55, v66, v67
	v_mul_f32_e32 v63, v143, v60
	v_mul_f32_e32 v64, v146, v62
	v_cndmask_b32_e64 v65, v64, v63, s[38:39]
	v_cndmask_b32_e32 v64, v60, v62, vcc
	v_pk_mul_f32 v[64:65], v[64:65], v[40:41]
	v_cmp_lt_i32_e32 vcc, 1, v61
	v_cmp_lt_i32_e64 s[38:39], 2, v61
	v_pk_mul_f32 v[40:41], v[132:133], v[60:61] op_sel_hi:[1,0]
	v_pk_mul_f32 v[60:61], v[134:135], v[62:63] op_sel_hi:[1,0]
	s_nop 0
	v_cndmask_b32_e64 v41, v61, v41, s[38:39]
	v_cndmask_b32_e32 v40, v60, v40, vcc
	v_pk_mul_f32 v[60:61], v[40:41], v[42:43]
	v_subrev_u32_e32 v41, 48, v147
	v_cvt_f32_i32_e32 v42, v41
	v_cmp_gt_i32_e32 vcc, 0, v41
	v_cmp_lt_i32_e64 s[38:39], 0, v41
	v_mul_f32_e64 v40, -v149, v42
	v_mul_f32_e32 v42, v150, v42
	v_exp_f32_e32 v40, v40
	v_exp_f32_e32 v42, v42
	v_mul_f32_e32 v43, v143, v40
	v_mul_f32_e32 v62, v146, v42
	v_cndmask_b32_e64 v63, v62, v43, s[38:39]
	v_cndmask_b32_e32 v62, v40, v42, vcc
	v_cmp_lt_i32_e32 vcc, 1, v41
	v_cmp_lt_i32_e64 s[38:39], 2, v41
	v_pk_mul_f32 v[40:41], v[132:133], v[40:41] op_sel_hi:[1,0]
	v_pk_mul_f32 v[42:43], v[134:135], v[42:43] op_sel_hi:[1,0]
	v_pk_mul_f32 v[44:45], v[62:63], v[44:45]
	v_cndmask_b32_e64 v41, v43, v41, s[38:39]
	v_cndmask_b32_e32 v40, v42, v40, vcc
	v_pk_mul_f32 v[46:47], v[40:41], v[46:47]
	v_subrev_u32_e32 v41, 56, v147
	v_cvt_f32_i32_e32 v42, v41
	v_cmp_gt_i32_e32 vcc, 0, v41
	v_cmp_lt_i32_e64 s[38:39], 0, v41
	v_mul_f32_e64 v40, -v149, v42
	v_mul_f32_e32 v42, v150, v42
	v_exp_f32_e32 v40, v40
	v_exp_f32_e32 v42, v42
	v_mul_f32_e32 v43, v143, v40
	v_mul_f32_e32 v62, v146, v42
	v_cndmask_b32_e64 v63, v62, v43, s[38:39]
	v_cndmask_b32_e32 v62, v40, v42, vcc
	v_cmp_lt_i32_e32 vcc, 1, v41
	v_cmp_lt_i32_e64 s[38:39], 2, v41
	v_pk_mul_f32 v[40:41], v[132:133], v[40:41] op_sel_hi:[1,0]
	v_pk_mul_f32 v[42:43], v[134:135], v[42:43] op_sel_hi:[1,0]
	v_pk_mul_f32 v[48:49], v[62:63], v[48:49]
	v_cndmask_b32_e64 v41, v43, v41, s[38:39]
	v_cndmask_b32_e32 v40, v42, v40, vcc
	v_pk_mul_f32 v[50:51], v[40:41], v[50:51]
	v_cvt_pk_bf16_f32 v40, v36, v37
	v_cvt_pk_bf16_f32 v36, v44, v45
; __device__ __forceinline__ unsigned pkbf(float lo, float hi) { const f32x2r v = {lo, hi}; return __builtin_bit_cast(unsigned, __builtin_convertvector(v, bf16x2r)); }
; #define RMFMA(a, b, c) __builtin_amdgcn_mfma_f32_32x32x16_bf16(a, b, c, 0, 0, 0)
; __device__ __forceinline__ void out_unit(RLAS unsigned char* L, int b, int h, int c, const bf16_t* QR, bf16_t* PR, const bf16_t* KR, const bf16_t* VR, const bf16_t* GR, const bf16_t* ST, size_t stbatch, const float* gnw, float lgf, float lgb, OutRegs& PF, bool is_first, bool has_next, int nb, int nh ...
;     ...
;       for (int jb = 0; jb < 4; ++jb) {
; #pragma unroll
;           for (int q4 = 0; q4 < 4; ++q4) {
;               const int d0 = iq - (32 * jb + 8 * q4 + 4 * h2); const float fd = (float)d0, Ff = __builtin_amdgcn_exp2f(lgf * fd), Fb = __builtin_amdgcn_exp2f(-lgb * fd);
;               X[jb][4 * q4 + 0] *= d0 >= 0 ? Ff : Fb;             X[jb][4 * q4 + 1] *= d0 >= 1 ? Ff * cfm[0] : Fb * cbp[0];
;               X[jb][4 * q4 + 2] *= d0 >= 2 ? Ff * cfm[1] : Fb * cbp[1]; X[jb][4 * q4 + 3] *= d0 >= 3 ? Ff * cfm[2] : Fb * cbp[2]; }
; #pragma unroll
;           for (int s = 0; s < 2; ++s) { u32x4 pw; pw.x = pkbf(X[jb][8 * s + 0], X[jb][8 * s + 1]); pw.y = pkbf(X[jb][8 * s + 2], X[jb][8 * s + 3]); pw.z = pkbf(X[jb][8 * s + 4], X[jb][8 * s + 5]); pw.w = pkbf(X[jb][8 * s + 6], X[jb][8 * s + 7]);
;               P[jb][s] = __builtin_bit_cast(bf16x8, pw); } } }
;     f32x16 Z[2];
; #pragma unroll
;     for (int t = 0; t < 2; ++t)
; #pragma unroll
;         for (int g = 0; g < 16; ++g) Z[t][g] = 0.f;
;     { const int cb0 = (64 * dvh + 16 * gq + 4 * p) * 2;
; #pragma unroll
;       for (int jb = 0; jb < 4; ++jb)
; #pragma unroll
;           for (int s = 0; s < 2; ++s) { const bf16x8 v0 = trfragv(R1, 32 * jb + 16 * s + 4 * h2 + q, 8, cb0), v1 = trfragv(R1, 32 * jb + 16 * s + 4 * h2 + q, 8, cb0 + 64);
;               Z[0] = RMFMA(P[jb][s], v0, Z[0]); Z[1] = RMFMA(P[jb][s], v1, Z[1]); } }
	v_subrev_u32_e32 v45, 64, v147
	v_cvt_pk_bf16_f32 v37, v46, v47
	v_cvt_f32_i32_e32 v46, v45
	v_cvt_pk_bf16_f32 v41, v38, v39
	v_cvt_pk_bf16_f32 v38, v48, v49
	v_cmp_gt_i32_e32 vcc, 0, v45
	v_mul_f32_e64 v44, -v149, v46
	v_mul_f32_e32 v46, v150, v46
	v_exp_f32_e32 v44, v44
	v_exp_f32_e32 v46, v46
	v_cmp_lt_i32_e64 s[38:39], 0, v45
	v_cvt_pk_bf16_f32 v43, v60, v61
	v_mul_f32_e32 v47, v143, v44
	v_mul_f32_e32 v48, v146, v46
	v_cndmask_b32_e64 v49, v48, v47, s[38:39]
	v_cndmask_b32_e32 v48, v44, v46, vcc
	v_cmp_lt_i32_e32 vcc, 1, v45
	v_cmp_lt_i32_e64 s[38:39], 2, v45
	v_pk_mul_f32 v[44:45], v[132:133], v[44:45] op_sel_hi:[1,0]
	v_pk_mul_f32 v[46:47], v[134:135], v[46:47] op_sel_hi:[1,0]
	v_pk_mul_f32 v[20:21], v[48:49], v[20:21]
	v_cndmask_b32_e64 v45, v47, v45, s[38:39]
	v_cndmask_b32_e32 v44, v46, v44, vcc
	v_pk_mul_f32 v[22:23], v[44:45], v[22:23]
	v_add_u32_e32 v45, 0xffffffb8, v147
	v_cvt_f32_i32_e32 v46, v45
	v_cmp_gt_i32_e32 vcc, 0, v45
	v_cmp_lt_i32_e64 s[38:39], 0, v45
	v_cvt_pk_bf16_f32 v60, v20, v21
	v_mul_f32_e64 v44, -v149, v46
	v_mul_f32_e32 v46, v150, v46
	v_exp_f32_e32 v44, v44
	v_exp_f32_e32 v46, v46
	v_add_u32_e32 v21, 0xffffffa0, v147
	v_cvt_pk_bf16_f32 v61, v22, v23
	v_mul_f32_e32 v47, v143, v44
	v_mul_f32_e32 v48, v146, v46
	v_cndmask_b32_e64 v49, v48, v47, s[38:39]
	v_cndmask_b32_e32 v48, v44, v46, vcc
	v_cmp_lt_i32_e32 vcc, 1, v45
	v_cmp_lt_i32_e64 s[38:39], 2, v45
	v_pk_mul_f32 v[44:45], v[132:133], v[44:45] op_sel_hi:[1,0]
	v_pk_mul_f32 v[46:47], v[134:135], v[46:47] op_sel_hi:[1,0]
	v_pk_mul_f32 v[24:25], v[48:49], v[24:25]
	v_cndmask_b32_e64 v45, v47, v45, s[38:39]
	v_cndmask_b32_e32 v44, v46, v44, vcc
	v_pk_mul_f32 v[26:27], v[44:45], v[26:27]
	v_add_u32_e32 v45, 0xffffffb0, v147
	v_cvt_f32_i32_e32 v46, v45
	v_cmp_gt_i32_e32 vcc, 0, v45
	v_cmp_lt_i32_e64 s[38:39], 0, v45
	v_cvt_f32_i32_e32 v22, v21
	v_mul_f32_e64 v44, -v149, v46
	v_mul_f32_e32 v46, v150, v46
	v_exp_f32_e32 v44, v44
	v_exp_f32_e32 v46, v46
	v_mul_f32_e64 v20, -v149, v22
	v_mul_f32_e32 v22, v150, v22
	v_mul_f32_e32 v47, v143, v44
	v_mul_f32_e32 v48, v146, v46
	v_cndmask_b32_e64 v49, v48, v47, s[38:39]
	v_cndmask_b32_e32 v48, v44, v46, vcc
	v_cmp_lt_i32_e32 vcc, 1, v45
	v_cmp_lt_i32_e64 s[38:39], 2, v45
	v_pk_mul_f32 v[44:45], v[132:133], v[44:45] op_sel_hi:[1,0]
	v_pk_mul_f32 v[46:47], v[134:135], v[46:47] op_sel_hi:[1,0]
	v_exp_f32_e32 v20, v20
	v_cndmask_b32_e64 v45, v47, v45, s[38:39]
	v_cndmask_b32_e32 v44, v46, v44, vcc
	v_pk_mul_f32 v[30:31], v[44:45], v[30:31]
	v_add_u32_e32 v45, 0xffffffa8, v147
	v_cvt_f32_i32_e32 v46, v45
	v_exp_f32_e32 v22, v22
	v_pk_mul_f32 v[28:29], v[48:49], v[28:29]
	v_cmp_gt_i32_e32 vcc, 0, v45
	v_mul_f32_e64 v44, -v149, v46
	v_mul_f32_e32 v46, v150, v46
	v_exp_f32_e32 v44, v44
	v_exp_f32_e32 v46, v46
	v_cmp_lt_i32_e64 s[38:39], 0, v45
	v_cvt_pk_bf16_f32 v62, v24, v25
	v_mul_f32_e32 v47, v143, v44
	v_mul_f32_e32 v48, v146, v46
	v_cndmask_b32_e64 v49, v48, v47, s[38:39]
	v_cndmask_b32_e32 v48, v44, v46, vcc
	v_cmp_lt_i32_e32 vcc, 1, v45
	v_cmp_lt_i32_e64 s[38:39], 2, v45
	v_pk_mul_f32 v[44:45], v[132:133], v[44:45] op_sel_hi:[1,0]
	v_pk_mul_f32 v[46:47], v[134:135], v[46:47] op_sel_hi:[1,0]
	v_mul_f32_e32 v23, v143, v20
	v_cndmask_b32_e64 v45, v47, v45, s[38:39]
	v_cndmask_b32_e32 v44, v46, v44, vcc
	v_mul_f32_e32 v24, v146, v22
	v_cmp_gt_i32_e32 vcc, 0, v21
	v_cmp_lt_i32_e64 s[38:39], 0, v21
	v_cvt_pk_bf16_f32 v42, v64, v65
	v_cvt_pk_bf16_f32 v39, v50, v51
	v_cndmask_b32_e64 v25, v24, v23, s[38:39]
	v_cndmask_b32_e32 v24, v20, v22, vcc
	v_cmp_lt_i32_e32 vcc, 1, v21
	v_cmp_lt_i32_e64 s[38:39], 2, v21
	v_pk_mul_f32 v[20:21], v[132:133], v[20:21] op_sel_hi:[1,0]
	v_pk_mul_f32 v[22:23], v[134:135], v[22:23] op_sel_hi:[1,0]
	v_pk_mul_f32 v[4:5], v[24:25], v[4:5]
	v_cndmask_b32_e64 v21, v23, v21, s[38:39]
	v_cndmask_b32_e32 v20, v22, v20, vcc
	v_pk_mul_f32 v[6:7], v[20:21], v[6:7]
	v_add_u32_e32 v21, 0xffffff98, v147
	v_cvt_f32_i32_e32 v22, v21
	v_cmp_gt_i32_e32 vcc, 0, v21
	v_cmp_lt_i32_e64 s[38:39], 0, v21
	v_cvt_pk_bf16_f32 v64, v4, v5
	v_mul_f32_e64 v20, -v149, v22
	v_mul_f32_e32 v22, v150, v22
	v_exp_f32_e32 v20, v20
	v_exp_f32_e32 v22, v22
	v_lshlrev_b32_e32 v4, 2, v140
	v_and_b32_e32 v4, 12, v4
	v_mul_f32_e32 v23, v143, v20
	v_mul_f32_e32 v24, v146, v22
	v_cndmask_b32_e64 v25, v24, v23, s[38:39]
	v_cndmask_b32_e32 v24, v20, v22, vcc
	v_cmp_lt_i32_e32 vcc, 1, v21
	v_cmp_lt_i32_e64 s[38:39], 2, v21
	v_pk_mul_f32 v[20:21], v[132:133], v[20:21] op_sel_hi:[1,0]
	v_pk_mul_f32 v[22:23], v[134:135], v[22:23] op_sel_hi:[1,0]
	v_pk_mul_f32 v[8:9], v[24:25], v[8:9]
	v_cndmask_b32_e64 v21, v23, v21, s[38:39]
	v_cndmask_b32_e32 v20, v22, v20, vcc
	v_pk_mul_f32 v[10:11], v[20:21], v[10:11]
	v_add_u32_e32 v21, 0xffffff90, v147
	v_cvt_f32_i32_e32 v22, v21
	v_cmp_gt_i32_e32 vcc, 0, v21
	v_cmp_lt_i32_e64 s[38:39], 0, v21
	v_or3_b32 v4, v4, v142, s26
	v_mul_f32_e64 v20, -v149, v22
	v_mul_f32_e32 v22, v150, v22
	v_exp_f32_e32 v20, v20
	v_exp_f32_e32 v22, v22
	v_and_or_b32 v5, v141, 3, v153
	v_lshlrev_b32_e32 v4, 1, v4
	v_mul_f32_e32 v23, v143, v20
	v_mul_f32_e32 v24, v146, v22
	v_cndmask_b32_e64 v25, v24, v23, s[38:39]
	v_cndmask_b32_e32 v24, v20, v22, vcc
	v_cmp_lt_i32_e32 vcc, 1, v21
	v_cmp_lt_i32_e64 s[38:39], 2, v21
	v_pk_mul_f32 v[20:21], v[132:133], v[20:21] op_sel_hi:[1,0]
	v_pk_mul_f32 v[22:23], v[134:135], v[22:23] op_sel_hi:[1,0]
	v_pk_mul_f32 v[12:13], v[24:25], v[12:13]
	v_cndmask_b32_e64 v21, v23, v21, s[38:39]
	v_cndmask_b32_e32 v20, v22, v20, vcc
	v_pk_mul_f32 v[14:15], v[20:21], v[14:15]
	v_add_u32_e32 v21, 0xffffff88, v147
	v_cvt_f32_i32_e32 v22, v21
	v_cmp_gt_i32_e32 vcc, 0, v21
	v_cmp_lt_i32_e64 s[38:39], 0, v21
	v_mul_u32_u24_e32 v5, 0x140, v5
	v_mul_f32_e64 v20, -v149, v22
	v_mul_f32_e32 v22, v150, v22
	v_exp_f32_e32 v20, v20
	v_exp_f32_e32 v22, v22
	v_add3_u32 v140, 0, v5, v4
	v_cvt_pk_bf16_f32 v65, v6, v7
	v_mul_f32_e32 v23, v143, v20
	v_mul_f32_e32 v24, v146, v22
	v_cndmask_b32_e64 v25, v24, v23, s[38:39]
	v_cndmask_b32_e32 v24, v20, v22, vcc
	v_cmp_lt_i32_e32 vcc, 1, v21
	v_cmp_lt_i32_e64 s[38:39], 2, v21
	v_pk_mul_f32 v[20:21], v[132:133], v[20:21] op_sel_hi:[1,0]
	v_pk_mul_f32 v[22:23], v[134:135], v[22:23] op_sel_hi:[1,0]
	v_pk_mul_f32 v[16:17], v[24:25], v[16:17]
	v_cndmask_b32_e64 v21, v23, v21, s[38:39]
	v_cndmask_b32_e32 v20, v22, v20, vcc
	v_pk_mul_f32 v[18:19], v[20:21], v[18:19]
	ds_read_b64_tr_b16 v[4:5], v140 offset:34816
	ds_read_b64_tr_b16 v[6:7], v140 offset:37376
	ds_read_b64_tr_b16 v[20:21], v140 offset:34880
	ds_read_b64_tr_b16 v[22:23], v140 offset:37440
	ds_read_b64_tr_b16 v[172:173], v140 offset:39936
	ds_read_b64_tr_b16 v[174:175], v140 offset:42496
	ds_read_b64_tr_b16 v[176:177], v140 offset:40000
	ds_read_b64_tr_b16 v[178:179], v140 offset:42560
	v_pk_mul_f32 v[32:33], v[48:49], v[32:33]
	v_cvt_pk_bf16_f32 v66, v8, v9
	v_cvt_pk_bf16_f32 v67, v10, v11
	v_cvt_pk_bf16_f32 v48, v12, v13
	v_cvt_pk_bf16_f32 v49, v14, v15
	v_cvt_pk_bf16_f32 v50, v16, v17
	v_cvt_pk_bf16_f32 v51, v18, v19
	s_waitcnt lgkmcnt(6)
; #define RLAS __attribute__((address_space(3)))
; #define LBAR() do { asm volatile("s_waitcnt lgkmcnt(0)" ::: "memory"); __builtin_amdgcn_s_barrier(); asm volatile("" ::: "memory"); } while (0)
; #define RMFMA(a, b, c) __builtin_amdgcn_mfma_f32_32x32x16_bf16(a, b, c, 0, 0, 0)
; __device__ __forceinline__ void out_unit(RLAS unsigned char* L, int b, int h, int c, const bf16_t* QR, bf16_t* PR, const bf16_t* KR, const bf16_t* VR, const bf16_t* GR, const bf16_t* ST, size_t stbatch, const float* gnw, float lgf, float lgb, OutRegs& PF, bool is_first, bool has_next, int nb, int nh ...
;     ...
;     { const int cb0 = (64 * dvh + 16 * gq + 4 * p) * 2;
; #pragma unroll
;       for (int jb = 0; jb < 4; ++jb)
; #pragma unroll
;           for (int s = 0; s < 2; ++s) { const bf16x8 v0 = trfragv(R1, 32 * jb + 16 * s + 4 * h2 + q, 8, cb0), v1 = trfragv(R1, 32 * jb + 16 * s + 4 * h2 + q, 8, cb0 + 64);
;               Z[0] = RMFMA(P[jb][s], v0, Z[0]); Z[1] = RMFMA(P[jb][s], v1, Z[1]); } }
;     LBAR();
; #pragma unroll
;     for (int i = 0; i < 4; ++i) { *(RLAS u32x4*)(R0 + (grow + 4 * i) * RS + gch * 16) = sfr[i]; *(RLAS u32x4*)(R1 + (grow + 4 * i) * RS + gch * 16) = sbr[i]; }
;     LBAR();
;     u32x4 gwr[4];
;     { const bf16_t* gp0 = GR + (tok0 + grow) * GRP + h * 128 + gch * 8;
; #pragma unroll
;       for (int i = 0; i < 4; ++i) gwr[i] = *(const u32x4*)(gp0 + (size_t)(4 * i) * GRP); }
;     { f32x16 Yf[2], Yb[2];
; #pragma unroll
;       for (int t = 0; t < 2; ++t)
; #pragma unroll
;           for (int g = 0; g < 16; ++g) { Yf[t][g] = 0.f; Yb[t][g] = 0.f; }
;       const int rb0 = (64 * dvh + r) * RS + 16 * h2;
; #pragma unroll
;       for (int ks = 0; ks < 8; ++ks) {
;           const bf16x8 f0 = *(const RLAS bf16x8*)(R0 + rb0 + 32 * ks), f1 = *(const RLAS bf16x8*)(R0 + rb0 + 32 * RS + 32 * ks), b0 = *(const RLAS bf16x8*)(R1 + rb0 + 32 * ks), b1 = *(const RLAS bf16x8*)(R1 + rb0 + 32 * RS + 32 * ks);
;           Yf[0] = RMFMA(qf[ks], f0, Yf[0]); Yf[1] = RMFMA(qf[ks], f1, Yf[1]); Yb[0] = RMFMA(qf[ks], b0, Yb[0]); Yb[1] = RMFMA(qf[ks], b1, Yb[1]); }
	v_mfma_f32_32x32x16_bf16 v[4:19], v[56:59], v[4:7], 0
	v_mul_f32_e64 v34, v44, v34
	v_mul_f32_e64 v35, v45, v35
	v_cvt_pk_bf16_f32 v63, v26, v27
	v_cvt_pk_bf16_f32 v44, v28, v29
	v_cvt_pk_bf16_f32 v45, v30, v31
	v_cvt_pk_bf16_f32 v46, v32, v33
	v_cvt_pk_bf16_f32 v47, v34, v35
	v_add_u32_e32 v141, 0x8800, v140
	s_waitcnt lgkmcnt(4)
	v_mfma_f32_32x32x16_bf16 v[20:35], v[56:59], v[20:23], 0
	ds_read_b64_tr_b16 v[180:181], v140 offset:45056
	ds_read_b64_tr_b16 v[182:183], v140 offset:47616
	ds_read_b64_tr_b16 v[184:185], v140 offset:45120
	ds_read_b64_tr_b16 v[186:187], v140 offset:47680
	s_waitcnt lgkmcnt(6)
	v_mfma_f32_32x32x16_bf16 v[4:19], v[52:55], v[172:175], v[4:19]
	s_waitcnt lgkmcnt(4)
	v_mfma_f32_32x32x16_bf16 v[20:35], v[52:55], v[176:179], v[20:35]
	ds_read_b64_tr_b16 v[172:173], v140 offset:50176
	ds_read_b64_tr_b16 v[174:175], v140 offset:52736
	ds_read_b64_tr_b16 v[176:177], v140 offset:50240
	ds_read_b64_tr_b16 v[178:179], v140 offset:52800
	s_waitcnt lgkmcnt(6)
	v_mfma_f32_32x32x16_bf16 v[4:19], v[40:43], v[180:183], v[4:19]
	s_waitcnt lgkmcnt(4)
	v_mfma_f32_32x32x16_bf16 v[20:35], v[40:43], v[184:187], v[20:35]
	ds_read_b64_tr_b16 v[180:181], v140 offset:55296
	ds_read_b64_tr_b16 v[182:183], v140 offset:57856
	ds_read_b64_tr_b16 v[184:185], v140 offset:55360
	ds_read_b64_tr_b16 v[186:187], v140 offset:57920
	s_waitcnt lgkmcnt(6)
	v_mfma_f32_32x32x16_bf16 v[4:19], v[36:39], v[172:175], v[4:19]
	s_waitcnt lgkmcnt(4)
	v_mfma_f32_32x32x16_bf16 v[20:35], v[36:39], v[176:179], v[20:35]
	ds_read_b64_tr_b16 v[172:173], v140 offset:60416
	ds_read_b64_tr_b16 v[174:175], v140 offset:62976
	ds_read_b64_tr_b16 v[176:177], v140 offset:60480
	ds_read_b64_tr_b16 v[178:179], v140 offset:63040
	s_waitcnt lgkmcnt(6)
	v_mfma_f32_32x32x16_bf16 v[4:19], v[60:63], v[180:183], v[4:19]
	s_waitcnt lgkmcnt(4)
	v_mfma_f32_32x32x16_bf16 v[20:35], v[60:63], v[184:187], v[20:35]
	ds_read_b64_tr_b16 v[180:181], v141 offset:30720
	ds_read_b64_tr_b16 v[182:183], v141 offset:33280
	ds_read_b64_tr_b16 v[184:185], v141 offset:30784
	ds_read_b64_tr_b16 v[186:187], v141 offset:33344
	s_waitcnt lgkmcnt(6)
	v_mfma_f32_32x32x16_bf16 v[4:19], v[44:47], v[172:175], v[4:19]
	s_waitcnt lgkmcnt(4)
	v_mfma_f32_32x32x16_bf16 v[20:35], v[44:47], v[176:179], v[20:35]
	ds_read_b64_tr_b16 v[36:37], v141 offset:35840
	ds_read_b64_tr_b16 v[38:39], v141 offset:38400
	ds_read_b64_tr_b16 v[40:41], v141 offset:35904
	ds_read_b64_tr_b16 v[42:43], v141 offset:38464
	s_waitcnt lgkmcnt(6)
	v_mfma_f32_32x32x16_bf16 v[4:19], v[64:67], v[180:183], v[4:19]
	s_waitcnt lgkmcnt(4)
	v_mfma_f32_32x32x16_bf16 v[20:35], v[64:67], v[184:187], v[20:35]
	s_waitcnt lgkmcnt(0)
	s_barrier
	s_waitcnt vmcnt(7)
	ds_write_b128 v136, v[72:75]
	s_waitcnt vmcnt(6)
	ds_write_b128 v136, v[76:79] offset:34816
	s_waitcnt vmcnt(5)
	ds_write_b128 v137, v[80:83]
	s_waitcnt vmcnt(4)
	ds_write_b128 v137, v[84:87] offset:34816
	s_waitcnt vmcnt(3)
	ds_write_b128 v138, v[88:91]
	s_waitcnt vmcnt(2)
	ds_write_b128 v138, v[92:95] offset:34816
	s_waitcnt vmcnt(1)
	ds_write_b128 v139, v[96:99]
	s_waitcnt vmcnt(0)
	ds_write_b128 v139, v[128:131] offset:34816
	s_waitcnt lgkmcnt(0)
	s_barrier
	s_waitcnt lgkmcnt(10)
	v_mfma_f32_32x32x16_bf16 v[4:19], v[48:51], v[36:39], v[4:19]
	v_lshl_add_u64 v[36:37], s[6:7], 0, v[144:145]
	v_readlane_b32 s6, v252, 32
	v_lshlrev_b64 v[146:147], 11, v[36:37]
	v_readlane_b32 s7, v252, 33
	s_nop 1
	v_lshl_add_u64 v[36:37], s[6:7], 0, v[146:147]
	v_lshl_add_u64 v[36:37], v[36:37], 0, s[16:17]
	v_lshl_add_u64 v[36:37], v[36:37], 0, v[2:3]
	s_movk_i32 s7, 0x2000
	v_add_co_u32_e32 v38, vcc, s7, v36
	s_movk_i32 s6, 0x4000
	s_nop 0
	v_addc_co_u32_e32 v39, vcc, 0, v37, vcc
	global_load_dwordx4 v[140:143], v[36:37], off
	global_load_dwordx4 v[136:139], v[38:39], off
	v_add_co_u32_e32 v38, vcc, s6, v36
	s_waitcnt lgkmcnt(8)
	v_mfma_f32_32x32x16_bf16 v[20:35], v[48:51], v[40:43], v[20:35]
	v_addc_co_u32_e32 v39, vcc, 0, v37, vcc
	v_add_co_u32_e32 v36, vcc, s27, v36
	global_load_dwordx4 v[132:135], v[38:39], off
	s_nop 0
	v_addc_co_u32_e32 v37, vcc, 0, v37, vcc
	global_load_dwordx4 v[128:131], v[36:37], off
	v_or_b32_e32 v36, s26, v151
	v_mad_u32_u24 v145, v36, s33, v152
	ds_read_b128 v[36:39], v145 offset:8704
	ds_read_b128 v[72:75], v145 offset:34816
	ds_read_b128 v[76:79], v145 offset:43520
	ds_read_b128 v[40:43], v145
	ds_read_b128 v[154:157], v145 offset:32
	s_waitcnt lgkmcnt(1)
	v_mfma_f32_32x32x16_bf16 v[52:67], v[68:71], v[40:43], 0
	ds_read_b128 v[158:161], v145 offset:8736
	ds_read_b128 v[162:165], v145 offset:34848
	ds_read_b128 v[166:169], v145 offset:43552
	v_mfma_f32_32x32x16_bf16 v[36:51], v[68:71], v[36:39], 0
	v_mfma_f32_32x32x16_bf16 v[84:99], v[68:71], v[72:75], 0
	v_mfma_f32_32x32x16_bf16 v[68:83], v[68:71], v[76:79], 0
	ds_read_b128 v[172:175], v145 offset:64
	ds_read_b128 v[176:179], v145 offset:8768
	ds_read_b128 v[180:183], v145 offset:34880
	ds_read_b128 v[184:187], v145 offset:43584
	s_waitcnt lgkmcnt(7)
	v_mfma_f32_32x32x16_bf16 v[52:67], v[124:127], v[154:157], v[52:67]
	s_waitcnt lgkmcnt(6)
	v_mfma_f32_32x32x16_bf16 v[36:51], v[124:127], v[158:161], v[36:51]
	s_waitcnt lgkmcnt(5)
	v_mfma_f32_32x32x16_bf16 v[84:99], v[124:127], v[162:165], v[84:99]
	s_waitcnt lgkmcnt(4)
	v_mfma_f32_32x32x16_bf16 v[68:83], v[124:127], v[166:169], v[68:83]
	ds_read_b128 v[154:157], v145 offset:96
	ds_read_b128 v[158:161], v145 offset:8800
	ds_read_b128 v[162:165], v145 offset:34912
	ds_read_b128 v[166:169], v145 offset:43616
	s_waitcnt lgkmcnt(7)
	v_mfma_f32_32x32x16_bf16 v[52:67], v[120:123], v[172:175], v[52:67]
	s_waitcnt lgkmcnt(6)
	v_mfma_f32_32x32x16_bf16 v[36:51], v[120:123], v[176:179], v[36:51]
	s_waitcnt lgkmcnt(5)
; #define RLAS __attribute__((address_space(3)))
; #define RMFMA(a, b, c) __builtin_amdgcn_mfma_f32_32x32x16_bf16(a, b, c, 0, 0, 0)
; __device__ __forceinline__ void out_unit(RLAS unsigned char* L, int b, int h, int c, const bf16_t* QR, bf16_t* PR, const bf16_t* KR, const bf16_t* VR, const bf16_t* GR, const bf16_t* ST, size_t stbatch, const float* gnw, float lgf, float lgb, OutRegs& PF, bool is_first, bool has_next, int nb, int nh ...
;     ...
;       for (int ks = 0; ks < 8; ++ks) {
;           const bf16x8 f0 = *(const RLAS bf16x8*)(R0 + rb0 + 32 * ks), f1 = *(const RLAS bf16x8*)(R0 + rb0 + 32 * RS + 32 * ks), b0 = *(const RLAS bf16x8*)(R1 + rb0 + 32 * ks), b1 = *(const RLAS bf16x8*)(R1 + rb0 + 32 * RS + 32 * ks);
;           Yf[0] = RMFMA(qf[ks], f0, Yf[0]); Yf[1] = RMFMA(qf[ks], f1, Yf[1]); Yb[0] = RMFMA(qf[ks], b0, Yb[0]); Yb[1] = RMFMA(qf[ks], b1, Yb[1]); }
; #pragma unroll
;       for (int q4 = 0; q4 < 4; ++q4) { const int il0 = 32 * ib + 8 * q4 + 4 * h2;
;           const float sf0 = __builtin_amdgcn_exp2f(lgf * (float)(il0 + 1)), sb0 = __builtin_amdgcn_exp2f(lgb * (float)(128 - il0));
; #pragma unroll
;           for (int e = 0; e < 4; ++e) { const float sf = e ? sf0 * __builtin_amdgcn_exp2f(lgf * (float)e) : sf0, sb = e ? sb0 * __builtin_amdgcn_exp2f(-lgb * (float)e) : sb0; const int g = 4 * q4 + e;
; #pragma unroll
;               for (int t = 0; t < 2; ++t) Z[t][g] += sf * Yf[t][g] + sb * Yb[t][g]; } } }
	v_mfma_f32_32x32x16_bf16 v[84:99], v[120:123], v[180:183], v[84:99]
	s_waitcnt lgkmcnt(4)
	v_mfma_f32_32x32x16_bf16 v[68:83], v[120:123], v[184:187], v[68:83]
	ds_read_b128 v[172:175], v145 offset:128
	ds_read_b128 v[176:179], v145 offset:8832
	ds_read_b128 v[180:183], v145 offset:34944
	ds_read_b128 v[184:187], v145 offset:43648
	s_waitcnt lgkmcnt(7)
	v_mfma_f32_32x32x16_bf16 v[52:67], v[116:119], v[154:157], v[52:67]
	s_waitcnt lgkmcnt(6)
	v_mfma_f32_32x32x16_bf16 v[36:51], v[116:119], v[158:161], v[36:51]
	s_waitcnt lgkmcnt(5)
	v_mfma_f32_32x32x16_bf16 v[84:99], v[116:119], v[162:165], v[84:99]
	s_waitcnt lgkmcnt(4)
	v_mfma_f32_32x32x16_bf16 v[68:83], v[116:119], v[166:169], v[68:83]
	ds_read_b128 v[154:157], v145 offset:160
	ds_read_b128 v[158:161], v145 offset:8864
	ds_read_b128 v[162:165], v145 offset:34976
	ds_read_b128 v[166:169], v145 offset:43680
	s_waitcnt lgkmcnt(7)
	v_mfma_f32_32x32x16_bf16 v[52:67], v[112:115], v[172:175], v[52:67]
	s_waitcnt lgkmcnt(6)
	v_mfma_f32_32x32x16_bf16 v[36:51], v[112:115], v[176:179], v[36:51]
	s_waitcnt lgkmcnt(5)
	v_mfma_f32_32x32x16_bf16 v[84:99], v[112:115], v[180:183], v[84:99]
	s_waitcnt lgkmcnt(4)
	v_mfma_f32_32x32x16_bf16 v[68:83], v[112:115], v[184:187], v[68:83]
	ds_read_b128 v[172:175], v145 offset:192
	ds_read_b128 v[176:179], v145 offset:8896
	ds_read_b128 v[180:183], v145 offset:35008
	ds_read_b128 v[184:187], v145 offset:43712
	s_waitcnt lgkmcnt(7)
	v_mfma_f32_32x32x16_bf16 v[52:67], v[108:111], v[154:157], v[52:67]
	s_waitcnt lgkmcnt(6)
	v_mfma_f32_32x32x16_bf16 v[36:51], v[108:111], v[158:161], v[36:51]
	s_waitcnt lgkmcnt(5)
	v_mfma_f32_32x32x16_bf16 v[84:99], v[108:111], v[162:165], v[84:99]
	s_waitcnt lgkmcnt(4)
	v_mfma_f32_32x32x16_bf16 v[68:83], v[108:111], v[166:169], v[68:83]
	ds_read_b128 v[154:157], v145 offset:224
	ds_read_b128 v[158:161], v145 offset:8928
	ds_read_b128 v[162:165], v145 offset:35040
	ds_read_b128 v[166:169], v145 offset:43744
	s_waitcnt lgkmcnt(7)
	v_mfma_f32_32x32x16_bf16 v[52:67], v[104:107], v[172:175], v[52:67]
	s_waitcnt lgkmcnt(6)
	v_mfma_f32_32x32x16_bf16 v[36:51], v[104:107], v[176:179], v[36:51]
	s_waitcnt lgkmcnt(5)
	v_mfma_f32_32x32x16_bf16 v[84:99], v[104:107], v[180:183], v[84:99]
	s_waitcnt lgkmcnt(4)
	v_mfma_f32_32x32x16_bf16 v[68:83], v[104:107], v[184:187], v[68:83]
	s_waitcnt lgkmcnt(0)
	s_barrier
	s_waitcnt lgkmcnt(3)
	v_mfma_f32_32x32x16_bf16 v[52:67], v[100:103], v[154:157], v[52:67]
	s_waitcnt lgkmcnt(2)
	v_mfma_f32_32x32x16_bf16 v[36:51], v[100:103], v[158:161], v[36:51]
	s_waitcnt lgkmcnt(1)
	v_mfma_f32_32x32x16_bf16 v[84:99], v[100:103], v[162:165], v[84:99]
	s_waitcnt lgkmcnt(0)
	v_mfma_f32_32x32x16_bf16 v[68:83], v[100:103], v[166:169], v[68:83]
	v_or_b32_e32 v100, s14, v153
	v_sub_u32_e32 v102, 0x80, v100
	v_or_b32_e32 v101, 1, v100
	v_cvt_f32_i32_e32 v102, v102
	v_cvt_f32_i32_e32 v101, v101
	s_movk_i32 s14, 0x210
	v_mul_f32_e64 v102, -v150, v102
	v_mul_f32_e64 v101, -v149, v101
	v_exp_f32_e32 v102, v102
	v_exp_f32_e32 v101, v101
	v_mul_f32_e32 v84, v102, v84
	v_fmac_f32_e32 v84, v101, v52
	v_mul_f32_e32 v52, v102, v68
	v_exp_f32_e32 v68, v150
	v_fmac_f32_e32 v52, v101, v36
	v_exp_f32_e64 v36, -v149
	v_add_f32_e32 v4, v4, v84
	v_mul_f32_e32 v84, v68, v102
	v_add_f32_e32 v20, v20, v52
	v_mul_f32_e32 v52, v36, v101
	v_mul_f32_e32 v85, v84, v85
	v_fmac_f32_e32 v85, v52, v53
	v_mul_f32_e32 v53, v84, v69
	v_fmac_f32_e32 v53, v52, v37
	v_add_f32_e32 v21, v21, v53
	v_add_f32_e32 v53, v150, v150
	v_mul_f32_e32 v37, -2.0, v149
	v_exp_f32_e32 v53, v53
	v_exp_f32_e32 v37, v37
	v_add_f32_e32 v5, v5, v85
	v_mul_f32_e32 v69, v53, v102
	v_mul_f32_e32 v52, v37, v101
	v_mul_f32_e32 v84, v69, v86
	v_fmac_f32_e32 v84, v52, v54
	v_mul_f32_e32 v54, v69, v70
	v_fmac_f32_e32 v54, v52, v38
	v_add_f32_e32 v22, v22, v54
	v_mul_f32_e32 v54, 0x40400000, v150
	v_mul_f32_e32 v38, 0xc0400000, v149
	v_exp_f32_e32 v54, v54
	v_exp_f32_e32 v38, v38
	v_add_f32_e32 v6, v6, v84
	v_mul_f32_e32 v69, v54, v102
	v_mul_f32_e32 v52, v38, v101
	v_mul_f32_e32 v70, v69, v87
	v_fmac_f32_e32 v70, v52, v55
	v_mul_f32_e32 v55, v69, v71
	v_fmac_f32_e32 v55, v52, v39
	v_sub_u32_e32 v52, 0x78, v100
	v_or_b32_e32 v39, 9, v100
	v_cvt_f32_i32_e32 v52, v52
	v_cvt_f32_i32_e32 v39, v39
	v_add_f32_e32 v23, v23, v55
	v_add_f32_e32 v7, v7, v70
	v_mul_f32_e64 v52, -v150, v52
	v_mul_f32_e64 v39, -v149, v39
	v_exp_f32_e32 v52, v52
	v_exp_f32_e32 v39, v39
	v_mul_f32_e32 v55, v52, v88
	v_fmac_f32_e32 v55, v39, v56
	v_add_f32_e32 v8, v8, v55
	v_mul_f32_e32 v55, v52, v72
	v_fmac_f32_e32 v55, v39, v40
	v_add_f32_e32 v24, v24, v55
	v_mul_f32_e32 v55, v68, v52
	v_mul_f32_e32 v40, v36, v39
	v_mul_f32_e32 v56, v55, v89
	v_mul_f32_e32 v55, v55, v73
	v_fmac_f32_e32 v55, v40, v41
	v_mul_f32_e32 v41, v53, v52
	v_fmac_f32_e32 v56, v40, v57
	v_add_f32_e32 v25, v25, v55
	v_mul_f32_e32 v40, v37, v39
	v_mul_f32_e32 v55, v41, v90
	v_mul_f32_e32 v41, v41, v74
	v_fmac_f32_e32 v55, v40, v58
	v_fmac_f32_e32 v41, v40, v42
	v_mul_f32_e32 v40, v54, v52
	v_add_f32_e32 v26, v26, v41
	v_mul_f32_e32 v39, v38, v39
	v_mul_f32_e32 v41, v40, v91
	v_mul_f32_e32 v40, v40, v75
	v_fmac_f32_e32 v40, v39, v43
	v_add_f32_e32 v27, v27, v40
	v_sub_u32_e32 v40, 0x70, v100
	v_fmac_f32_e32 v41, v39, v59
	v_or_b32_e32 v39, 17, v100
	v_cvt_f32_i32_e32 v40, v40
	v_cvt_f32_i32_e32 v39, v39
	v_add_f32_e32 v11, v11, v41
	v_add_f32_e32 v9, v9, v56
	v_mul_f32_e64 v40, -v150, v40
	v_mul_f32_e64 v39, -v149, v39
	v_exp_f32_e32 v40, v40
	v_exp_f32_e32 v39, v39
	v_add_f32_e32 v10, v10, v55
	v_mul_f32_e32 v41, v40, v92
	v_fmac_f32_e32 v41, v39, v60
	v_add_f32_e32 v12, v12, v41
	v_mul_f32_e32 v41, v40, v76
	v_fmac_f32_e32 v41, v39, v44
; __device__ __forceinline__ int crow(int r,int hi){return (r&3)+8*(r>>2)+4*hi;}
; #define RLAS __attribute__((address_space(3)))
; __device__ __forceinline__ int crow(int g, int hi) { return (g & 3) + 8 * (g >> 2) + 4 * hi; }
; #define LBAR() do { asm volatile("s_waitcnt lgkmcnt(0)" ::: "memory"); __builtin_amdgcn_s_barrier(); asm volatile("" ::: "memory"); } while (0)
; __device__ __forceinline__ void out_prefetch(OutRegs& R, int b, int h, int c, const bf16_t* QR, const bf16_t* KR, const bf16_t* VR) {
;     int tid_ = threadIdx.x; asm volatile("" : "+v"(tid_));
;     const int grow = (tid_ >> 6) * 16 + ((tid_ >> 4) & 3), gch = tid_ & 15; const size_t tok0 = (size_t)b * SEQ + (size_t)c * 128;
;     const bf16_t* kp = KR + (tok0 + grow) * 512 + h * 128 + gch * 8; const bf16_t* vp = VR + (tok0 + grow) * 512 + h * 128 + gch * 8; const bf16_t* qp = QR + (tok0 + grow) * QRP + h * 128 + gch * 8;
; #pragma unroll
;     for (int i = 0; i < 4; ++i) { R.q[i] = *(const u32x4*)(qp + (size_t)(4 * i) * QRP); R.k[i] = *(const u32x4*)(kp + (size_t)(4 * i) * 512); R.v[i] = *(const u32x4*)(vp + (size_t)(4 * i) * 512); }
; }
; __device__ __forceinline__ void out_unit(RLAS unsigned char* L, int b, int h, int c, const bf16_t* QR, bf16_t* PR, const bf16_t* KR, const bf16_t* VR, const bf16_t* GR, const bf16_t* ST, size_t stbatch, const float* gnw, float lgf, float lgb, OutRegs& PF, bool is_first, bool has_next, int nb, int nh ...
;     ...
;     LBAR();
;     { RLAS float* Os = (RLAS float*)L;
; #pragma unroll
;       for (int t = 0; t < 2; ++t)
; #pragma unroll
;           for (int g = 0; g < 16; ++g) Os[(32 * ib + crow(g, h2)) * OS + 64 * dvh + 32 * t + r] = Z[t][g]; }
;     LBAR();
;     asm volatile("" ::: "memory"); __builtin_amdgcn_sched_barrier(0);
;     f32x4 w0 = *(const f32x4*)(gnw + h * 128 + gch * 8), w1 = *(const f32x4*)(gnw + h * 128 + gch * 8 + 4);
;     asm volatile("" : "+v"(w0), "+v"(w1));
;     out_prefetch(PF, has_next ? nb : b, has_next ? nh : h, has_next ? nc : c, QR, KR, VR);
;     { const int cb = h * 128 + gch * 8;
;       f32x4 o[4][2]; float sm[4], vq[4];
; #pragma unroll
;       for (int i = 0; i < 4; ++i) { const RLAS float* Os = (const RLAS float*)L + (grow + 4 * i) * OS + gch * 8; o[i][0] = *(const RLAS f32x4*)Os; o[i][1] = *(const RLAS f32x4*)(Os + 4);
	v_mul_f32_e32 v42, v68, v40
	v_add_f32_e32 v28, v28, v41
	v_mul_f32_e32 v41, v36, v39
	v_mul_f32_e32 v43, v42, v93
	v_mul_f32_e32 v42, v42, v77
	v_fmac_f32_e32 v42, v41, v45
	v_fmac_f32_e32 v43, v41, v61
	v_add_f32_e32 v29, v29, v42
	v_mul_f32_e32 v42, v53, v40
	v_add_f32_e32 v13, v13, v43
	v_mul_f32_e32 v41, v37, v39
	v_mul_f32_e32 v43, v42, v94
	v_mul_f32_e32 v42, v42, v78
	v_mul_f32_e32 v40, v54, v40
	v_fmac_f32_e32 v43, v41, v62
	v_fmac_f32_e32 v42, v41, v46
	v_mul_f32_e32 v39, v38, v39
	v_mul_f32_e32 v41, v40, v95
	v_mul_f32_e32 v40, v40, v79
	v_fmac_f32_e32 v40, v39, v47
	v_add_f32_e32 v31, v31, v40
	v_sub_u32_e32 v40, 0x68, v100
	v_fmac_f32_e32 v41, v39, v63
	v_or_b32_e32 v39, 25, v100
	v_cvt_f32_i32_e32 v40, v40
	v_cvt_f32_i32_e32 v39, v39
	v_add_f32_e32 v15, v15, v41
	v_add_f32_e32 v30, v30, v42
	v_mul_f32_e64 v40, -v150, v40
	v_mul_f32_e64 v39, -v149, v39
	v_exp_f32_e32 v40, v40
	v_exp_f32_e32 v39, v39
	v_add_f32_e32 v14, v14, v43
	v_mul_f32_e32 v41, v40, v96
	v_fmac_f32_e32 v41, v39, v64
	v_add_f32_e32 v16, v16, v41
	v_mul_f32_e32 v41, v40, v80
	v_fmac_f32_e32 v41, v39, v48
	v_add_f32_e32 v32, v32, v41
	v_mul_f32_e32 v41, v68, v40
	v_mul_f32_e32 v36, v36, v39
	v_mul_f32_e32 v42, v41, v97
	v_mul_f32_e32 v41, v41, v81
	v_fmac_f32_e32 v42, v36, v65
	v_fmac_f32_e32 v41, v36, v49
	v_mul_f32_e32 v36, v37, v39
	v_mul_f32_e32 v37, v53, v40
	v_add_f32_e32 v33, v33, v41
	v_mul_f32_e32 v41, v37, v98
	v_mul_f32_e32 v37, v37, v82
	v_fmac_f32_e32 v37, v36, v50
	v_add_f32_e32 v34, v34, v37
	v_mul_f32_e32 v37, v54, v40
	v_fmac_f32_e32 v41, v36, v66
	v_mul_f32_e32 v36, v38, v39
	v_mul_f32_e32 v38, v37, v99
	v_mul_f32_e32 v37, v37, v83
	v_fmac_f32_e32 v37, v36, v51
	v_fmac_f32_e32 v38, v36, v67
	v_add_f32_e32 v35, v35, v37
	v_lshlrev_b32_e32 v36, 2, v151
	v_mul_lo_u32 v37, v100, s14
	v_add3_u32 v36, s1, v36, v37
	ds_write2_b32 v36, v4, v20 offset1:32
	ds_write2_b32 v36, v5, v21 offset0:132 offset1:164
	v_add_u32_e32 v4, 0x400, v36
	ds_write2_b32 v4, v6, v22 offset0:8 offset1:40
	ds_write2_b32 v4, v7, v23 offset0:140 offset1:172
	v_add_u32_e32 v4, 0x1000, v36
	ds_write2_b32 v4, v8, v24 offset0:32 offset1:64
	ds_write2_b32 v4, v9, v25 offset0:164 offset1:196
	v_add_u32_e32 v4, 0x1400, v36
	ds_write2_b32 v4, v10, v26 offset0:40 offset1:72
	ds_write2_b32 v4, v11, v27 offset0:172 offset1:204
	v_add_u32_e32 v4, 0x2000, v36
	ds_write2_b32 v4, v12, v28 offset0:64 offset1:96
	ds_write2_b32 v4, v13, v29 offset0:196 offset1:228
	v_add_u32_e32 v4, 0x2400, v36
	ds_write2_b32 v4, v14, v30 offset0:72 offset1:104
	ds_write2_b32 v4, v15, v31 offset0:204 offset1:236
	v_add_u32_e32 v4, 0x3000, v36
	v_add_f32_e32 v17, v17, v42
	ds_write2_b32 v4, v16, v32 offset0:96 offset1:128
	v_add_u32_e32 v4, 0x3200, v36
	v_add_f32_e32 v18, v18, v41
	ds_write2_b32 v4, v17, v33 offset0:100 offset1:132
	v_add_u32_e32 v4, 0x3400, v36
	v_add_f32_e32 v19, v19, v38
	ds_write2_b32 v4, v18, v34 offset0:104 offset1:136
	v_add_u32_e32 v4, 0x3600, v36
	ds_write2_b32 v4, v19, v35 offset0:108 offset1:140
	s_waitcnt lgkmcnt(0)
	s_barrier
	v_lshlrev_b32_e32 v60, 5, v148
	global_load_dwordx4 v[52:55], v60, s[4:5] offset:16
	global_load_dwordx4 v[56:59], v60, s[4:5]
	s_cselect_b32 s0, s21, s0
	v_mov_b32_e32 v10, v0
	s_cselect_b32 s4, s22, s15
	s_cselect_b32 s5, s23, s20
	s_ashr_i32 s1, s0, 31
	s_lshl_b64 s[0:1], s[0:1], 12
	s_lshl_b32 s5, s5, 7
	s_or_b32 s0, s0, s5
	v_mov_b32_e32 v11, v3
	v_mul_lo_u32 v61, v144, s14
	v_add3_u32 v92, 0, v60, v61
	v_or_b32_e32 v2, s16, v2
	s_add_i32 s12, s12, 1
	s_add_i32 s13, s13, s3
	s_waitcnt vmcnt(0)
	s_nop 0
	v_ashrrev_i32_e32 v4, 2, v10
	v_bfe_u32 v5, v10, 4, 2
	v_and_or_b32 v4, v4, -16, v5
	v_ashrrev_i32_e32 v5, 31, v4
	v_lshl_add_u64 v[4:5], s[0:1], 0, v[4:5]
	v_lshlrev_b64 v[6:7], 10, v[4:5]
	v_lshlrev_b64 v[4:5], 11, v[4:5]
	s_lshl_b32 s0, s4, 8
	s_mov_b32 s1, s17
	v_lshlrev_b32_e32 v10, 4, v10
	v_lshl_add_u64 v[4:5], s[82:83], 0, v[4:5]
	v_and_b32_e32 v10, 0xf0, v10
	v_lshl_add_u64 v[4:5], v[4:5], 0, s[0:1]
	v_lshl_add_u64 v[8:9], s[92:93], 0, v[6:7]
	v_readlane_b32 s4, v252, 30
	v_lshl_add_u64 v[24:25], v[4:5], 0, v[10:11]
	v_lshl_add_u64 v[8:9], v[8:9], 0, s[0:1]
	v_readlane_b32 s5, v252, 31
	v_add_co_u32_e32 v12, vcc, s7, v24
	v_lshl_add_u64 v[44:45], v[8:9], 0, v[10:11]
	v_lshl_add_u64 v[6:7], s[4:5], 0, v[6:7]
	v_addc_co_u32_e32 v13, vcc, 0, v25, vcc
	v_lshl_add_u64 v[6:7], v[6:7], 0, s[0:1]
	v_add_co_u32_e32 v26, vcc, s7, v44
	v_lshl_add_u64 v[46:47], v[6:7], 0, v[10:11]
	s_nop 0
	v_addc_co_u32_e32 v27, vcc, 0, v45, vcc
	v_add_co_u32_e32 v36, vcc, s7, v46
	global_load_dwordx4 v[16:19], v[24:25], off
	global_load_dwordx4 v[4:7], v[44:45], off
	global_load_dwordx4 v[8:11], v[46:47], off
	v_addc_co_u32_e32 v37, vcc, 0, v47, vcc
	v_add_co_u32_e32 v32, vcc, s6, v24
	s_movk_i32 s0, 0x3000
	s_nop 0
	v_addc_co_u32_e32 v33, vcc, 0, v25, vcc
	v_add_co_u32_e32 v24, vcc, s27, v24
	global_load_dwordx4 v[12:15], v[12:13], off
	s_nop 0
	v_addc_co_u32_e32 v25, vcc, 0, v25, vcc
	v_add_co_u32_e32 v44, vcc, s0, v44
	global_load_dwordx4 v[20:23], v[26:27], off offset:-4096
	s_nop 0
	v_addc_co_u32_e32 v45, vcc, 0, v45, vcc
	global_load_dwordx4 v[28:31], v[36:37], off offset:-4096
	global_load_dwordx4 v[40:43], v[32:33], off
	s_nop 0
	global_load_dwordx4 v[32:35], v[26:27], off
	s_nop 0
	global_load_dwordx4 v[36:39], v[36:37], off
	s_nop 0
	global_load_dwordx4 v[24:27], v[24:25], off
	s_nop 0
	global_load_dwordx4 v[48:51], v[44:45], off
	v_add_co_u32_e32 v44, vcc, s0, v46
	s_mov_b32 s0, 0x358637bd
	s_nop 0
	v_addc_co_u32_e32 v45, vcc, 0, v47, vcc
	global_load_dwordx4 v[44:47], v[44:45], off
	ds_read_b128 v[80:83], v92
	ds_read_b128 v[76:79], v92 offset:16
	ds_read_b128 v[88:91], v92 offset:2112
	ds_read_b128 v[84:87], v92 offset:2128
	ds_read_b128 v[72:75], v92 offset:4224
	ds_read_b128 v[68:71], v92 offset:4240
	s_waitcnt lgkmcnt(5)
; #define RLAS __attribute__((address_space(3)))
; __device__ __forceinline__ void out_unit(RLAS unsigned char* L, int b, int h, int c, const bf16_t* QR, bf16_t* PR, const bf16_t* KR, const bf16_t* VR, const bf16_t* GR, const bf16_t* ST, size_t stbatch, const float* gnw, float lgf, float lgb, OutRegs& PF, bool is_first, bool has_next, int nb, int nh ...
;     ...
;       for (int i = 0; i < 4; ++i) { const RLAS float* Os = (const RLAS float*)L + (grow + 4 * i) * OS + gch * 8; o[i][0] = *(const RLAS f32x4*)Os; o[i][1] = *(const RLAS f32x4*)(Os + 4);
;           sm[i] = ((o[i][0][0] + o[i][0][1]) + (o[i][0][2] + o[i][0][3])) + ((o[i][1][0] + o[i][1][1]) + (o[i][1][2] + o[i][1][3])); }
; #pragma unroll
;       for (int i = 0; i < 4; ++i) sm[i] = row16_sum(sm[i]);
; #pragma unroll
;       for (int i = 0; i < 4; ++i) { const float mean = sm[i] * (1.f / 128.f); o[i][0] = o[i][0] - mean; o[i][1] = o[i][1] - mean;
;           vq[i] = ((o[i][0][0] * o[i][0][0] + o[i][0][1] * o[i][0][1]) + (o[i][0][2] * o[i][0][2] + o[i][0][3] * o[i][0][3])) + ((o[i][1][0] * o[i][1][0] + o[i][1][1] * o[i][1][1]) + (o[i][1][2] * o[i][1][2] + o[i][1][3] * o[i][1][3])); }
; #pragma unroll
;       for (int i = 0; i < 4; ++i) vq[i] = row16_sum(vq[i]);
	v_mov_b32_e32 v60, v80
	s_waitcnt lgkmcnt(4)
	v_mov_b32_e32 v61, v76
	v_mov_b32_e32 v62, v81
	v_mov_b32_e32 v63, v77
	v_pk_add_f32 v[60:61], v[60:61], v[62:63]
	v_mov_b32_e32 v62, v82
	v_mov_b32_e32 v63, v78
	v_mov_b32_e32 v64, v83
	v_mov_b32_e32 v65, v79
	v_pk_add_f32 v[62:63], v[62:63], v[64:65]
	s_waitcnt lgkmcnt(3)
	v_mov_b32_e32 v64, v91
	v_pk_add_f32 v[60:61], v[60:61], v[62:63]
	v_mov_b32_e32 v62, v89
	v_add_f32_e32 v98, v60, v61
	v_mov_b32_e32 v60, v88
	s_waitcnt lgkmcnt(2)
	v_mov_b32_e32 v61, v84
	v_mov_b32_e32 v63, v85
	v_pk_add_f32 v[60:61], v[60:61], v[62:63]
	v_mov_b32_e32 v62, v90
	v_mov_b32_e32 v63, v86
	v_mov_b32_e32 v65, v87
	v_pk_add_f32 v[62:63], v[62:63], v[64:65]
	s_waitcnt lgkmcnt(1)
	v_mov_b32_e32 v64, v75
	v_pk_add_f32 v[60:61], v[60:61], v[62:63]
	v_mov_b32_e32 v62, v73
	v_add_f32_e32 v99, v60, v61
	v_mov_b32_e32 v60, v72
	s_waitcnt lgkmcnt(0)
	v_mov_b32_e32 v61, v68
	v_mov_b32_e32 v63, v69
	v_pk_add_f32 v[60:61], v[60:61], v[62:63]
	v_mov_b32_e32 v62, v74
	v_mov_b32_e32 v63, v70
	v_mov_b32_e32 v65, v71
	v_pk_add_f32 v[62:63], v[62:63], v[64:65]
	s_nop 0
	v_pk_add_f32 v[60:61], v[60:61], v[62:63]
	s_nop 0
	v_add_f32_e32 v100, v60, v61
	ds_read_b128 v[64:67], v92 offset:6336
	ds_read_b128 v[60:63], v92 offset:6352
	s_waitcnt lgkmcnt(1)
	v_mov_b32_e32 v92, v64
	s_waitcnt lgkmcnt(0)
	v_mov_b32_e32 v93, v60
	v_mov_b32_e32 v94, v65
	v_mov_b32_e32 v95, v61
	v_pk_add_f32 v[92:93], v[92:93], v[94:95]
	v_mov_b32_e32 v94, v66
	v_mov_b32_e32 v95, v62
	v_mov_b32_e32 v96, v67
	v_mov_b32_e32 v97, v63
	v_pk_add_f32 v[94:95], v[94:95], v[96:97]
	s_nop 0
	v_pk_add_f32 v[92:93], v[92:93], v[94:95]
	v_add_f32_dpp v94, v99, v99 quad_perm:[1,0,3,2] row_mask:0xf bank_mask:0xf bound_ctrl:1
	v_add_f32_e32 v92, v92, v93
	v_add_f32_dpp v93, v98, v98 quad_perm:[1,0,3,2] row_mask:0xf bank_mask:0xf bound_ctrl:1
	v_add_f32_dpp v94, v94, v94 quad_perm:[2,3,0,1] row_mask:0xf bank_mask:0xf bound_ctrl:1
	v_add_f32_dpp v92, v92, v92 quad_perm:[1,0,3,2] row_mask:0xf bank_mask:0xf bound_ctrl:1
	v_add_f32_dpp v93, v93, v93 quad_perm:[2,3,0,1] row_mask:0xf bank_mask:0xf bound_ctrl:1
	v_add_f32_dpp v94, v94, v94 row_half_mirror row_mask:0xf bank_mask:0xf bound_ctrl:1
	v_add_f32_dpp v92, v92, v92 quad_perm:[2,3,0,1] row_mask:0xf bank_mask:0xf bound_ctrl:1
	v_add_f32_dpp v93, v93, v93 row_half_mirror row_mask:0xf bank_mask:0xf bound_ctrl:1
	v_add_f32_dpp v102, v94, v94 row_mirror row_mask:0xf bank_mask:0xf bound_ctrl:1
	v_add_f32_dpp v92, v92, v92 row_half_mirror row_mask:0xf bank_mask:0xf bound_ctrl:1
	v_add_f32_dpp v93, v93, v93 row_mirror row_mask:0xf bank_mask:0xf bound_ctrl:1
	v_fmamk_f32 v81, v93, 0xbc000000, v81
	v_fmamk_f32 v77, v93, 0xbc000000, v77
	v_fmamk_f32 v99, v93, 0xbc000000, v83
	v_fmamk_f32 v98, v93, 0xbc000000, v82
	v_fmac_f32_e32 v80, 0xbc000000, v93
	v_fmamk_f32 v97, v93, 0xbc000000, v79
	v_fmac_f32_e32 v76, 0xbc000000, v93
	v_mov_b32_e32 v82, v81
	v_mov_b32_e32 v83, v77
	v_add_f32_dpp v104, v92, v92 row_mirror row_mask:0xf bank_mask:0xf bound_ctrl:1
	v_fmamk_f32 v96, v93, 0xbc000000, v78
	v_mov_b32_e32 v78, v80
	v_mov_b32_e32 v79, v76
	v_pk_mul_f32 v[82:83], v[82:83], v[82:83]
	v_mov_b32_e32 v92, v99
	v_mov_b32_e32 v93, v97
	v_add_f32_dpp v94, v100, v100 quad_perm:[1,0,3,2] row_mask:0xf bank_mask:0xf bound_ctrl:1
	v_pk_fma_f32 v[78:79], v[78:79], v[78:79], v[82:83]
	v_mov_b32_e32 v82, v98
	v_mov_b32_e32 v83, v96
	v_pk_mul_f32 v[92:93], v[92:93], v[92:93]
	v_add_f32_dpp v94, v94, v94 quad_perm:[2,3,0,1] row_mask:0xf bank_mask:0xf bound_ctrl:1
	v_pk_fma_f32 v[82:83], v[82:83], v[82:83], v[92:93]
	v_fmamk_f32 v89, v102, 0xbc000000, v89
	v_fmamk_f32 v85, v102, 0xbc000000, v85
	v_add_f32_dpp v94, v94, v94 row_half_mirror row_mask:0xf bank_mask:0xf bound_ctrl:1
	v_pk_add_f32 v[100:101], v[78:79], v[82:83]
	v_fmamk_f32 v93, v102, 0xbc000000, v91
	v_fmac_f32_e32 v88, 0xbc000000, v102
	v_fmamk_f32 v95, v102, 0xbc000000, v87
	v_fmac_f32_e32 v84, 0xbc000000, v102
	v_mov_b32_e32 v82, v89
	v_mov_b32_e32 v83, v85
	v_add_f32_dpp v103, v94, v94 row_mirror row_mask:0xf bank_mask:0xf bound_ctrl:1
	v_fmamk_f32 v92, v102, 0xbc000000, v90
	v_fmamk_f32 v94, v102, 0xbc000000, v86
	v_mov_b32_e32 v78, v88
	v_mov_b32_e32 v79, v84
	v_pk_mul_f32 v[82:83], v[82:83], v[82:83]
	v_mov_b32_e32 v86, v93
	v_mov_b32_e32 v87, v95
	v_pk_fma_f32 v[78:79], v[78:79], v[78:79], v[82:83]
	v_mov_b32_e32 v82, v92
	v_mov_b32_e32 v83, v94
	v_pk_mul_f32 v[86:87], v[86:87], v[86:87]
	v_fmamk_f32 v73, v103, 0xbc000000, v73
	v_pk_fma_f32 v[82:83], v[82:83], v[82:83], v[86:87]
	v_fmamk_f32 v69, v103, 0xbc000000, v69
	v_pk_add_f32 v[90:91], v[78:79], v[82:83]
	v_fmamk_f32 v75, v103, 0xbc000000, v75
	v_fmac_f32_e32 v72, 0xbc000000, v103
	v_fmamk_f32 v79, v103, 0xbc000000, v71
	v_fmac_f32_e32 v68, 0xbc000000, v103
	v_mov_b32_e32 v82, v73
	v_mov_b32_e32 v83, v69
	v_fmamk_f32 v74, v103, 0xbc000000, v74
	v_fmamk_f32 v78, v103, 0xbc000000, v70
	v_mov_b32_e32 v70, v72
	v_mov_b32_e32 v71, v68
	v_pk_mul_f32 v[82:83], v[82:83], v[82:83]
	v_mov_b32_e32 v86, v75
	v_mov_b32_e32 v87, v79
	v_pk_fma_f32 v[70:71], v[70:71], v[70:71], v[82:83]
	v_mov_b32_e32 v82, v74
	v_mov_b32_e32 v83, v78
	v_pk_mul_f32 v[86:87], v[86:87], v[86:87]
	v_fmamk_f32 v65, v104, 0xbc000000, v65
	v_pk_fma_f32 v[82:83], v[82:83], v[82:83], v[86:87]
	v_fmamk_f32 v61, v104, 0xbc000000, v61
	v_pk_add_f32 v[82:83], v[70:71], v[82:83]
	v_fmamk_f32 v67, v104, 0xbc000000, v67
	v_fmac_f32_e32 v64, 0xbc000000, v104
	v_fmamk_f32 v71, v104, 0xbc000000, v63
	v_fmac_f32_e32 v60, 0xbc000000, v104
	v_mov_b32_e32 v86, v65
	v_mov_b32_e32 v87, v61
	v_fmamk_f32 v66, v104, 0xbc000000, v66
	v_fmamk_f32 v70, v104, 0xbc000000, v62
	v_mov_b32_e32 v62, v64
;       #define SILU_(x) ((x)*__builtin_amdgcn_rcpf(1.f+__builtin_amdgcn_exp2f(-1.4426950408889634f*(x))))
; __device__ __forceinline__ unsigned pkbf(float lo, float hi) { const f32x2r v = {lo, hi}; return __builtin_bit_cast(unsigned, __builtin_convertvector(v, bf16x2r)); }
; #define SILU_(x) ((x) * __builtin_amdgcn_rcpf(1.f + __builtin_amdgcn_exp2f(-1.4426950408889634f * (x))))
; __device__ __forceinline__ void out_unit(RLAS unsigned char* L, int b, int h, int c, const bf16_t* QR, bf16_t* PR, const bf16_t* KR, const bf16_t* VR, const bf16_t* GR, const bf16_t* ST, size_t stbatch, const float* gnw, float lgf, float lgb, OutRegs& PF, bool is_first, bool has_next, int nb, int nh ...
;     ...
;       for (int i = 0; i < 4; ++i) { const float mean = sm[i] * (1.f / 128.f); o[i][0] = o[i][0] - mean; o[i][1] = o[i][1] - mean;
;           vq[i] = ((o[i][0][0] * o[i][0][0] + o[i][0][1] * o[i][0][1]) + (o[i][0][2] * o[i][0][2] + o[i][0][3] * o[i][0][3])) + ((o[i][1][0] * o[i][1][0] + o[i][1][1] * o[i][1][1]) + (o[i][1][2] * o[i][1][2] + o[i][1][3] * o[i][1][3])); }
; #pragma unroll
;       for (int i = 0; i < 4; ++i) vq[i] = row16_sum(vq[i]);
;       bf16_t* op = PR + (tok0 + grow) * QRP + cb;
; #pragma unroll
;       for (int i = 0; i < 4; ++i) { const float rstd = rsqrtf(vq[i] * (1.f / 128.f) + EPS); const u32x4 gw = gwr[i];
;           const f32x4 a0 = o[i][0] * rstd * w0, a1 = o[i][1] * rstd * w1; u32x4 ow;
;     ...
;           const float g0 = __uint_as_float(gw.x << 16), g1 = __uint_as_float(gw.x & 0xffff0000u), g2 = __uint_as_float(gw.y << 16), g3 = __uint_as_float(gw.y & 0xffff0000u), g4 = __uint_as_float(gw.z << 16), g5 = __uint_as_float(gw.z & 0xffff0000u), g6 = __uint_as_float(gw.w << 16), g7 = __uint_as_float(gw.w & 0xffff0000u);
;           ow.x = pkbf(a0[0] * SILU_(g0), a0[1] * SILU_(g1)); ow.y = pkbf(a0[2] * SILU_(g2), a0[3] * SILU_(g3));
;           ow.z = pkbf(a1[0] * SILU_(g4), a1[1] * SILU_(g5)); ow.w = pkbf(a1[2] * SILU_(g6), a1[3] * SILU_(g7));
;     ...
;           *(u32x4*)(op + (size_t)(4 * i) * QRP) = ow; } }
	v_mov_b32_e32 v63, v60
	v_pk_mul_f32 v[86:87], v[86:87], v[86:87]
	v_mov_b32_e32 v102, v67
	v_mov_b32_e32 v103, v71
	v_pk_fma_f32 v[62:63], v[62:63], v[62:63], v[86:87]
	v_mov_b32_e32 v86, v66
	v_mov_b32_e32 v87, v70
	v_pk_mul_f32 v[102:103], v[102:103], v[102:103]
	s_nop 0
	v_pk_fma_f32 v[86:87], v[86:87], v[86:87], v[102:103]
	v_lshlrev_b32_e32 v102, 16, v140
	v_pk_add_f32 v[86:87], v[62:63], v[86:87]
	v_lshl_add_u64 v[62:63], s[82:83], 0, v[146:147]
	v_lshl_add_u64 v[62:63], v[62:63], 0, v[2:3]
	v_mul_f32_e32 v2, 0xbfb8aa3b, v102
	v_exp_f32_e32 v2, v2
	v_and_b32_e32 v103, 0xffff0000, v140
	v_add_f32_e32 v2, 1.0, v2
	v_rcp_f32_e32 v104, v2
	v_mul_f32_e32 v2, 0xbfb8aa3b, v103
	v_exp_f32_e32 v2, v2
	s_nop 0
	v_add_f32_e32 v2, 1.0, v2
	v_rcp_f32_e32 v105, v2
	s_nop 0
	v_pk_mul_f32 v[102:103], v[104:105], v[102:103]
	v_lshlrev_b32_e32 v104, 16, v141
	v_mul_f32_e32 v2, 0xbfb8aa3b, v104
	v_exp_f32_e32 v2, v2
	v_and_b32_e32 v105, 0xffff0000, v141
	v_add_f32_e32 v2, 1.0, v2
	v_rcp_f32_e32 v106, v2
	v_mul_f32_e32 v2, 0xbfb8aa3b, v105
	v_exp_f32_e32 v2, v2
	s_nop 0
	v_add_f32_e32 v2, 1.0, v2
	v_rcp_f32_e32 v107, v2
	s_nop 0
	v_pk_mul_f32 v[104:105], v[106:107], v[104:105]
	v_lshlrev_b32_e32 v106, 16, v142
	v_mul_f32_e32 v2, 0xbfb8aa3b, v106
	v_exp_f32_e32 v2, v2
	v_and_b32_e32 v107, 0xffff0000, v142
	v_add_f32_e32 v2, 1.0, v2
	v_rcp_f32_e32 v108, v2
	v_mul_f32_e32 v2, 0xbfb8aa3b, v107
	v_exp_f32_e32 v2, v2
	s_nop 0
	v_add_f32_e32 v2, 1.0, v2
	v_rcp_f32_e32 v109, v2
	s_nop 0
	v_pk_mul_f32 v[106:107], v[108:109], v[106:107]
	v_lshlrev_b32_e32 v108, 16, v143
	v_mul_f32_e32 v2, 0xbfb8aa3b, v108
	v_exp_f32_e32 v2, v2
	v_and_b32_e32 v109, 0xffff0000, v143
	v_add_f32_e32 v2, 1.0, v2
	v_rcp_f32_e32 v110, v2
	v_mul_f32_e32 v2, 0xbfb8aa3b, v109
	v_exp_f32_e32 v2, v2
	s_nop 0
	v_add_f32_e32 v2, 1.0, v2
	v_rcp_f32_e32 v111, v2
	s_nop 0
	v_pk_mul_f32 v[108:109], v[110:111], v[108:109]
	v_mov_b32_e32 v110, v90
	v_mov_b32_e32 v111, v100
	v_mov_b32_e32 v100, v91
	v_pk_add_f32 v[90:91], v[110:111], v[100:101]
	s_nop 1
	v_mov_b32_dpp v101, v91 quad_perm:[1,0,3,2] row_mask:0xf bank_mask:0xf bound_ctrl:1
	v_mov_b32_dpp v100, v90 quad_perm:[1,0,3,2] row_mask:0xf bank_mask:0xf bound_ctrl:1
	v_pk_add_f32 v[90:91], v[90:91], v[100:101]
	s_nop 1
	v_mov_b32_dpp v101, v91 quad_perm:[2,3,0,1] row_mask:0xf bank_mask:0xf bound_ctrl:1
	v_mov_b32_dpp v100, v90 quad_perm:[2,3,0,1] row_mask:0xf bank_mask:0xf bound_ctrl:1
	v_pk_add_f32 v[90:91], v[90:91], v[100:101]
	s_nop 1
	v_mov_b32_dpp v101, v91 row_half_mirror row_mask:0xf bank_mask:0xf bound_ctrl:1
	v_mov_b32_dpp v100, v90 row_half_mirror row_mask:0xf bank_mask:0xf bound_ctrl:1
	v_pk_add_f32 v[90:91], v[90:91], v[100:101]
	s_nop 1
	v_mov_b32_dpp v101, v91 row_mirror row_mask:0xf bank_mask:0xf bound_ctrl:1
	v_mov_b32_dpp v100, v90 row_mirror row_mask:0xf bank_mask:0xf bound_ctrl:1
	v_pk_add_f32 v[100:101], v[90:91], v[100:101]
	v_mov_b64_e32 v[90:91], s[0:1]
	s_brev_b32 s0, 60
	v_pk_fma_f32 v[100:101], v[100:101], s[0:1], v[90:91] op_sel_hi:[1,0,0]
	s_nop 0
	v_mul_f32_e32 v2, 0x4b800000, v101
	v_cmp_gt_f32_e64 s[38:39], s35, v101
	v_cmp_gt_f32_e32 vcc, s35, v100
	s_nop 0
	v_cndmask_b32_e64 v2, v101, v2, s[38:39]
	v_rsq_f32_e32 v2, v2
	s_nop 0
	v_mul_f32_e32 v101, 0x45800000, v2
	v_cndmask_b32_e64 v2, v2, v101, s[38:39]
	v_pk_mul_f32 v[80:81], v[80:81], v[2:3] op_sel_hi:[1,0]
	v_pk_mul_f32 v[98:99], v[98:99], v[2:3] op_sel_hi:[1,0]
	v_pk_mul_f32 v[76:77], v[76:77], v[2:3] op_sel_hi:[1,0]
	v_pk_mul_f32 v[96:97], v[96:97], v[2:3] op_sel_hi:[1,0]
	v_mul_f32_e32 v2, 0x4b800000, v100
	v_cndmask_b32_e32 v2, v100, v2, vcc
	v_rsq_f32_e32 v2, v2
	v_pk_mul_f32 v[80:81], v[56:57], v[80:81]
	v_pk_mul_f32 v[76:77], v[52:53], v[76:77]
	v_pk_mul_f32 v[98:99], v[58:59], v[98:99]
	v_pk_mul_f32 v[110:111], v[54:55], v[96:97]
	v_pk_mul_f32 v[80:81], v[102:103], v[80:81]
	v_pk_mul_f32 v[76:77], v[106:107], v[76:77]
	v_cvt_pk_bf16_f32 v96, v80, v81
	v_pk_mul_f32 v[80:81], v[104:105], v[98:99]
	v_cvt_pk_bf16_f32 v98, v76, v77
	v_pk_mul_f32 v[76:77], v[108:109], v[110:111]
	v_cvt_pk_bf16_f32 v97, v80, v81
	v_cvt_pk_bf16_f32 v99, v76, v77
	v_mul_f32_e32 v76, 0x45800000, v2
	v_cndmask_b32_e32 v2, v2, v76, vcc
	v_pk_mul_f32 v[80:81], v[92:93], v[2:3] op_sel_hi:[1,0]
	v_lshlrev_b32_e32 v92, 16, v136
	v_pk_mul_f32 v[76:77], v[88:89], v[2:3] op_sel_hi:[1,0]
	v_pk_mul_f32 v[84:85], v[84:85], v[2:3] op_sel_hi:[1,0]
	v_pk_mul_f32 v[88:89], v[94:95], v[2:3] op_sel_hi:[1,0]
	v_mul_f32_e32 v2, 0xbfb8aa3b, v92
	v_exp_f32_e32 v2, v2
	v_and_b32_e32 v93, 0xffff0000, v136
	v_pk_mul_f32 v[76:77], v[56:57], v[76:77]
	v_pk_mul_f32 v[80:81], v[58:59], v[80:81]
	v_add_f32_e32 v2, 1.0, v2
	v_rcp_f32_e32 v94, v2
	v_mul_f32_e32 v2, 0xbfb8aa3b, v93
	v_exp_f32_e32 v2, v2
	v_pk_mul_f32 v[84:85], v[52:53], v[84:85]
	v_pk_mul_f32 v[88:89], v[54:55], v[88:89]
	global_store_dwordx4 v[62:63], v[96:99], off
	v_add_f32_e32 v2, 1.0, v2
	v_rcp_f32_e32 v95, v2
	s_nop 0
	v_pk_mul_f32 v[92:93], v[94:95], v[92:93]
	s_nop 0
	v_pk_mul_f32 v[76:77], v[92:93], v[76:77]
	s_nop 0
	v_cvt_pk_bf16_f32 v92, v76, v77
	v_lshlrev_b32_e32 v76, 16, v137
	v_mul_f32_e32 v2, 0xbfb8aa3b, v76
	v_exp_f32_e32 v2, v2
	v_and_b32_e32 v77, 0xffff0000, v137
	v_add_f32_e32 v2, 1.0, v2
	v_rcp_f32_e32 v94, v2
	v_mul_f32_e32 v2, 0xbfb8aa3b, v77
	v_exp_f32_e32 v2, v2
	s_nop 0
	v_add_f32_e32 v2, 1.0, v2
	v_rcp_f32_e32 v95, v2
	s_nop 0
	v_pk_mul_f32 v[76:77], v[94:95], v[76:77]
	s_nop 0
	v_pk_mul_f32 v[76:77], v[76:77], v[80:81]
	s_nop 0
	v_cvt_pk_bf16_f32 v93, v76, v77
	v_lshlrev_b32_e32 v76, 16, v138
	v_mul_f32_e32 v2, 0xbfb8aa3b, v76
	v_exp_f32_e32 v2, v2
	v_and_b32_e32 v77, 0xffff0000, v138
	v_add_f32_e32 v2, 1.0, v2
;       #define SILU_(x) ((x)*__builtin_amdgcn_rcpf(1.f+__builtin_amdgcn_exp2f(-1.4426950408889634f*(x))))
; __device__ __forceinline__ unsigned pkbf(float lo, float hi) { const f32x2r v = {lo, hi}; return __builtin_bit_cast(unsigned, __builtin_convertvector(v, bf16x2r)); }
; #define LBAR() do { asm volatile("s_waitcnt lgkmcnt(0)" ::: "memory"); __builtin_amdgcn_s_barrier(); asm volatile("" ::: "memory"); } while (0)
; #define SILU_(x) ((x) * __builtin_amdgcn_rcpf(1.f + __builtin_amdgcn_exp2f(-1.4426950408889634f * (x))))
; __device__ __forceinline__ void out_unit(RLAS unsigned char* L, int b, int h, int c, const bf16_t* QR, bf16_t* PR, const bf16_t* KR, const bf16_t* VR, const bf16_t* GR, const bf16_t* ST, size_t stbatch, const float* gnw, float lgf, float lgb, OutRegs& PF, bool is_first, bool has_next, int nb, int nh ...
;     ...
;       for (int i = 0; i < 4; ++i) { const float rstd = rsqrtf(vq[i] * (1.f / 128.f) + EPS); const u32x4 gw = gwr[i];
;           const f32x4 a0 = o[i][0] * rstd * w0, a1 = o[i][1] * rstd * w1; u32x4 ow;
;     ...
;           const float g0 = __uint_as_float(gw.x << 16), g1 = __uint_as_float(gw.x & 0xffff0000u), g2 = __uint_as_float(gw.y << 16), g3 = __uint_as_float(gw.y & 0xffff0000u), g4 = __uint_as_float(gw.z << 16), g5 = __uint_as_float(gw.z & 0xffff0000u), g6 = __uint_as_float(gw.w << 16), g7 = __uint_as_float(gw.w & 0xffff0000u);
;           ow.x = pkbf(a0[0] * SILU_(g0), a0[1] * SILU_(g1)); ow.y = pkbf(a0[2] * SILU_(g2), a0[3] * SILU_(g3));
;           ow.z = pkbf(a1[0] * SILU_(g4), a1[1] * SILU_(g5)); ow.w = pkbf(a1[2] * SILU_(g6), a1[3] * SILU_(g7));
;     ...
;           *(u32x4*)(op + (size_t)(4 * i) * QRP) = ow; } }
;     LBAR();
	v_rcp_f32_e32 v80, v2
	v_mul_f32_e32 v2, 0xbfb8aa3b, v77
	v_exp_f32_e32 v2, v2
	s_nop 0
	v_add_f32_e32 v2, 1.0, v2
	v_rcp_f32_e32 v81, v2
	s_nop 0
	v_pk_mul_f32 v[76:77], v[80:81], v[76:77]
	s_nop 0
	v_pk_mul_f32 v[76:77], v[76:77], v[84:85]
	s_nop 0
	v_cvt_pk_bf16_f32 v94, v76, v77
	v_lshlrev_b32_e32 v76, 16, v139
	v_mul_f32_e32 v2, 0xbfb8aa3b, v76
	v_exp_f32_e32 v2, v2
	v_and_b32_e32 v77, 0xffff0000, v139
	v_add_f32_e32 v2, 1.0, v2
	v_rcp_f32_e32 v80, v2
	v_mul_f32_e32 v2, 0xbfb8aa3b, v77
	v_exp_f32_e32 v2, v2
	s_nop 0
	v_add_f32_e32 v2, 1.0, v2
	v_rcp_f32_e32 v81, v2
	s_nop 0
	v_pk_mul_f32 v[76:77], v[80:81], v[76:77]
	s_nop 0
	v_pk_mul_f32 v[76:77], v[76:77], v[88:89]
	s_nop 0
	v_cvt_pk_bf16_f32 v95, v76, v77
	v_add_co_u32_e32 v76, vcc, s7, v62
	s_nop 1
	v_addc_co_u32_e32 v77, vcc, 0, v63, vcc
	global_store_dwordx4 v[76:77], v[92:95], off
	v_lshlrev_b32_e32 v76, 16, v132
	v_mul_f32_e32 v2, 0xbfb8aa3b, v76
	v_exp_f32_e32 v2, v2
	v_and_b32_e32 v77, 0xffff0000, v132
	v_add_f32_e32 v2, 1.0, v2
	v_rcp_f32_e32 v80, v2
	v_mul_f32_e32 v2, 0xbfb8aa3b, v77
	v_exp_f32_e32 v2, v2
	s_nop 0
	v_add_f32_e32 v2, 1.0, v2
	v_rcp_f32_e32 v81, v2
	s_nop 0
	v_pk_mul_f32 v[76:77], v[80:81], v[76:77]
	v_lshlrev_b32_e32 v80, 16, v133
	v_mul_f32_e32 v2, 0xbfb8aa3b, v80
	v_exp_f32_e32 v2, v2
	v_and_b32_e32 v81, 0xffff0000, v133
	v_add_f32_e32 v2, 1.0, v2
	v_rcp_f32_e32 v84, v2
	v_mul_f32_e32 v2, 0xbfb8aa3b, v81
	v_exp_f32_e32 v2, v2
	s_nop 0
	v_add_f32_e32 v2, 1.0, v2
	v_rcp_f32_e32 v85, v2
	s_nop 0
	v_pk_mul_f32 v[80:81], v[84:85], v[80:81]
	v_lshlrev_b32_e32 v84, 16, v134
	v_mul_f32_e32 v2, 0xbfb8aa3b, v84
	v_exp_f32_e32 v2, v2
	v_and_b32_e32 v85, 0xffff0000, v134
	v_add_f32_e32 v2, 1.0, v2
	v_rcp_f32_e32 v88, v2
	v_mul_f32_e32 v2, 0xbfb8aa3b, v85
	v_exp_f32_e32 v2, v2
	s_nop 0
	v_add_f32_e32 v2, 1.0, v2
	v_rcp_f32_e32 v89, v2
	s_nop 0
	v_pk_mul_f32 v[84:85], v[88:89], v[84:85]
	v_lshlrev_b32_e32 v88, 16, v135
	v_mul_f32_e32 v2, 0xbfb8aa3b, v88
	v_exp_f32_e32 v2, v2
	v_and_b32_e32 v89, 0xffff0000, v135
	v_add_f32_e32 v2, 1.0, v2
	v_rcp_f32_e32 v92, v2
	v_mul_f32_e32 v2, 0xbfb8aa3b, v89
	v_exp_f32_e32 v2, v2
	s_nop 0
	v_add_f32_e32 v2, 1.0, v2
	v_rcp_f32_e32 v93, v2
	s_nop 0
	v_pk_mul_f32 v[88:89], v[92:93], v[88:89]
	v_mov_b32_e32 v92, v86
	v_mov_b32_e32 v93, v82
	v_mov_b32_e32 v82, v87
	v_pk_add_f32 v[82:83], v[92:93], v[82:83]
	s_nop 1
	v_mov_b32_dpp v87, v83 quad_perm:[1,0,3,2] row_mask:0xf bank_mask:0xf bound_ctrl:1
	v_mov_b32_dpp v86, v82 quad_perm:[1,0,3,2] row_mask:0xf bank_mask:0xf bound_ctrl:1
	v_pk_add_f32 v[82:83], v[82:83], v[86:87]
	s_nop 1
	v_mov_b32_dpp v87, v83 quad_perm:[2,3,0,1] row_mask:0xf bank_mask:0xf bound_ctrl:1
	v_mov_b32_dpp v86, v82 quad_perm:[2,3,0,1] row_mask:0xf bank_mask:0xf bound_ctrl:1
	v_pk_add_f32 v[82:83], v[82:83], v[86:87]
	s_nop 1
	v_mov_b32_dpp v87, v83 row_half_mirror row_mask:0xf bank_mask:0xf bound_ctrl:1
	v_mov_b32_dpp v86, v82 row_half_mirror row_mask:0xf bank_mask:0xf bound_ctrl:1
	v_pk_add_f32 v[82:83], v[82:83], v[86:87]
	s_nop 1
	v_mov_b32_dpp v87, v83 row_mirror row_mask:0xf bank_mask:0xf bound_ctrl:1
	v_mov_b32_dpp v86, v82 row_mirror row_mask:0xf bank_mask:0xf bound_ctrl:1
	v_pk_add_f32 v[82:83], v[82:83], v[86:87]
	s_nop 0
	v_pk_fma_f32 v[82:83], v[82:83], s[0:1], v[90:91] op_sel_hi:[1,0,0]
	s_mov_b64 s[0:1], 0
	v_mul_f32_e32 v2, 0x4b800000, v83
	v_cmp_gt_f32_e64 s[38:39], s35, v83
	v_cmp_gt_f32_e32 vcc, s35, v82
	s_nop 0
	v_cndmask_b32_e64 v2, v83, v2, s[38:39]
	v_rsq_f32_e32 v2, v2
	s_nop 0
	v_mul_f32_e32 v83, 0x45800000, v2
	v_cndmask_b32_e64 v2, v2, v83, s[38:39]
	v_pk_mul_f32 v[72:73], v[72:73], v[2:3] op_sel_hi:[1,0]
	v_pk_mul_f32 v[74:75], v[74:75], v[2:3] op_sel_hi:[1,0]
	v_pk_mul_f32 v[68:69], v[68:69], v[2:3] op_sel_hi:[1,0]
	v_pk_mul_f32 v[78:79], v[78:79], v[2:3] op_sel_hi:[1,0]
	v_mul_f32_e32 v2, 0x4b800000, v82
	v_pk_mul_f32 v[74:75], v[58:59], v[74:75]
	v_pk_mul_f32 v[72:73], v[56:57], v[72:73]
	v_pk_mul_f32 v[68:69], v[52:53], v[68:69]
	v_cndmask_b32_e32 v2, v82, v2, vcc
	v_pk_mul_f32 v[78:79], v[54:55], v[78:79]
	v_pk_mul_f32 v[72:73], v[76:77], v[72:73]
	v_pk_mul_f32 v[74:75], v[80:81], v[74:75]
	v_pk_mul_f32 v[68:69], v[84:85], v[68:69]
	v_rsq_f32_e32 v2, v2
	v_cvt_pk_bf16_f32 v72, v72, v73
	v_cvt_pk_bf16_f32 v73, v74, v75
	v_cvt_pk_bf16_f32 v74, v68, v69
	v_pk_mul_f32 v[68:69], v[88:89], v[78:79]
	s_nop 0
	v_cvt_pk_bf16_f32 v75, v68, v69
	v_add_co_u32_e64 v68, s[38:39], s6, v62
	s_nop 1
	v_addc_co_u32_e64 v69, s[38:39], 0, v63, s[38:39]
	global_store_dwordx4 v[68:69], v[72:75], off
	v_mul_f32_e32 v68, 0x45800000, v2
	v_cndmask_b32_e32 v2, v2, v68, vcc
	v_pk_mul_f32 v[64:65], v[64:65], v[2:3] op_sel_hi:[1,0]
	v_pk_mul_f32 v[60:61], v[60:61], v[2:3] op_sel_hi:[1,0]
	v_pk_mul_f32 v[56:57], v[56:57], v[64:65]
	v_pk_mul_f32 v[64:65], v[70:71], v[2:3] op_sel_hi:[1,0]
	v_pk_mul_f32 v[66:67], v[66:67], v[2:3] op_sel_hi:[1,0]
	v_pk_mul_f32 v[64:65], v[54:55], v[64:65]
	v_pk_mul_f32 v[54:55], v[52:53], v[60:61]
	v_lshlrev_b32_e32 v52, 16, v128
	v_mul_f32_e32 v2, 0xbfb8aa3b, v52
	v_exp_f32_e32 v2, v2
	v_and_b32_e32 v53, 0xffff0000, v128
	v_pk_mul_f32 v[58:59], v[58:59], v[66:67]
	v_add_f32_e32 v2, 1.0, v2
	v_rcp_f32_e32 v60, v2
	v_mul_f32_e32 v2, 0xbfb8aa3b, v53
	v_exp_f32_e32 v2, v2
	s_nop 0
	v_add_f32_e32 v2, 1.0, v2
	v_rcp_f32_e32 v61, v2
	s_nop 0
	v_pk_mul_f32 v[52:53], v[60:61], v[52:53]
	s_nop 0
	v_pk_mul_f32 v[52:53], v[52:53], v[56:57]
	v_lshlrev_b32_e32 v56, 16, v129
	v_mul_f32_e32 v2, 0xbfb8aa3b, v56
	v_exp_f32_e32 v2, v2
	v_and_b32_e32 v57, 0xffff0000, v129
	v_cvt_pk_bf16_f32 v52, v52, v53
	v_add_f32_e32 v2, 1.0, v2
	v_rcp_f32_e32 v60, v2
	v_mul_f32_e32 v2, 0xbfb8aa3b, v57
	v_exp_f32_e32 v2, v2
	s_nop 0
	v_add_f32_e32 v2, 1.0, v2
	v_rcp_f32_e32 v61, v2
	s_nop 0
	v_pk_mul_f32 v[56:57], v[60:61], v[56:57]
	s_nop 0
	v_pk_mul_f32 v[56:57], v[56:57], v[58:59]
	s_nop 0
	v_cvt_pk_bf16_f32 v53, v56, v57
	v_lshlrev_b32_e32 v56, 16, v130
	v_mul_f32_e32 v2, 0xbfb8aa3b, v56
	v_exp_f32_e32 v2, v2
	v_and_b32_e32 v57, 0xffff0000, v130
	v_add_f32_e32 v2, 1.0, v2
	v_rcp_f32_e32 v58, v2
	v_mul_f32_e32 v2, 0xbfb8aa3b, v57
	v_exp_f32_e32 v2, v2
	s_nop 0
	v_add_f32_e32 v2, 1.0, v2
	v_rcp_f32_e32 v59, v2
	s_nop 0
	v_pk_mul_f32 v[56:57], v[58:59], v[56:57]
	s_nop 0
	v_pk_mul_f32 v[54:55], v[56:57], v[54:55]
	v_lshlrev_b32_e32 v56, 16, v131
	v_mul_f32_e32 v2, 0xbfb8aa3b, v56
	v_exp_f32_e32 v2, v2
	v_and_b32_e32 v57, 0xffff0000, v131
	v_cvt_pk_bf16_f32 v54, v54, v55
	v_add_f32_e32 v2, 1.0, v2
	v_rcp_f32_e32 v58, v2
	v_mul_f32_e32 v2, 0xbfb8aa3b, v57
	v_exp_f32_e32 v2, v2
	s_nop 0
	v_add_f32_e32 v2, 1.0, v2
	v_rcp_f32_e32 v59, v2
	s_nop 0
	v_pk_mul_f32 v[56:57], v[58:59], v[56:57]
	s_nop 0
	v_pk_mul_f32 v[56:57], v[56:57], v[64:65]
	s_nop 0
	v_cvt_pk_bf16_f32 v55, v56, v57
	v_add_co_u32_e32 v56, vcc, 0x6000, v62
	s_nop 1
	v_addc_co_u32_e32 v57, vcc, 0, v63, vcc
	global_store_dwordx4 v[56:57], v[52:55], off
	s_waitcnt lgkmcnt(0)
	s_barrier
